# v14: v13 minus s_setprio 0 before the pre-barrier wait (loader stays at prio 2 until the MFMA block sets 1)
# baseline (speedup 1.0000x reference)
.LBB0_271:
	s_add_u32 s26, s14, 0xfffc0080
	s_addc_u32 s27, s15, -1
	s_add_i32 s54, 0, 0x10000
	s_cmp_eq_u32 s53, 12
	s_cselect_b32 s29, s21, s27
	s_cselect_b32 s28, s49, s26
	v_add_u32_e32 v154, s54, v141
	s_cselect_b32 s27, s19, s52
	s_cselect_b32 s26, s50, s51
	s_add_i32 s56, 0, 0x14000
	ds_read_b128 v[146:149], v154
	ds_read_b128 v[150:153], v154 offset:1024
	ds_read_b128 v[162:165], v154 offset:2048
	ds_read_b128 v[166:169], v154 offset:3072
	v_add_u32_e32 v154, s56, v141
	ds_read_b128 v[170:173], v154
	ds_read_b128 v[186:189], v154 offset:1024
	ds_read_b128 v[190:193], v154 offset:2048
	ds_read_b128 v[194:197], v154 offset:3072
	v_lshl_add_u64 v[154:155], s[14:15], 0, v[136:137]
	s_add_i32 m0, s37, 0xc000
	ds_read_b128 v[198:201], v145
	ds_read_b128 v[202:205], v145 offset:1024
	ds_read_b128 v[206:209], v145 offset:2048
	ds_read_b128 v[210:213], v145 offset:3072
	ds_read_b128 v[214:217], v145 offset:4096
	ds_read_b128 v[218:221], v145 offset:5120
	ds_read_b128 v[222:225], v145 offset:6144
	ds_read_b128 v[226:229], v145 offset:7168
	global_load_lds_dwordx4 v[154:155], off
	v_lshl_add_u64 v[154:155], s[14:15], 0, v[138:139]
	s_add_i32 m0, s37, 0xe000
	s_nop 0
	global_load_lds_dwordx4 v[154:155], off
	s_waitcnt vmcnt(8) lgkmcnt(0)
	s_barrier
	s_setprio 1
	v_mfma_f32_16x16x32_bf16 v[126:129], v[146:149], v[198:201], v[126:129]
	v_mfma_f32_16x16x32_bf16 v[122:125], v[162:165], v[198:201], v[122:125]
	v_mfma_f32_16x16x32_bf16 v[110:113], v[146:149], v[206:209], v[110:113]
	v_mfma_f32_16x16x32_bf16 v[106:109], v[162:165], v[206:209], v[106:109]
	v_mfma_f32_16x16x32_bf16 v[92:95], v[146:149], v[214:217], v[92:95]
	v_mfma_f32_16x16x32_bf16 v[88:91], v[162:165], v[214:217], v[88:91]
	v_mfma_f32_16x16x32_bf16 v[76:79], v[146:149], v[222:225], v[76:79]
	v_mfma_f32_16x16x32_bf16 v[72:75], v[162:165], v[222:225], v[72:75]
	v_mfma_f32_16x16x32_bf16 v[126:129], v[150:153], v[202:205], v[126:129]
	v_mfma_f32_16x16x32_bf16 v[122:125], v[166:169], v[202:205], v[122:125]
	v_mfma_f32_16x16x32_bf16 v[110:113], v[150:153], v[210:213], v[110:113]
	v_mfma_f32_16x16x32_bf16 v[106:109], v[166:169], v[210:213], v[106:109]
	v_mfma_f32_16x16x32_bf16 v[92:95], v[150:153], v[218:221], v[92:95]
	v_mfma_f32_16x16x32_bf16 v[88:91], v[166:169], v[218:221], v[88:91]
	v_mfma_f32_16x16x32_bf16 v[76:79], v[150:153], v[226:229], v[76:79]
	v_mfma_f32_16x16x32_bf16 v[72:75], v[166:169], v[226:229], v[72:75]
	s_setprio 0
	s_setprio 1
	v_mfma_f32_16x16x32_bf16 v[118:121], v[170:173], v[198:201], v[118:121]
	v_mfma_f32_16x16x32_bf16 v[114:117], v[190:193], v[198:201], v[114:117]
	v_mfma_f32_16x16x32_bf16 v[102:105], v[170:173], v[206:209], v[102:105]
	v_mfma_f32_16x16x32_bf16 v[98:101], v[190:193], v[206:209], v[98:101]
	v_mfma_f32_16x16x32_bf16 v[84:87], v[170:173], v[214:217], v[84:87]
	v_mfma_f32_16x16x32_bf16 v[80:83], v[190:193], v[214:217], v[80:83]
	v_mfma_f32_16x16x32_bf16 v[68:71], v[170:173], v[222:225], v[68:71]
	v_mfma_f32_16x16x32_bf16 v[64:67], v[190:193], v[222:225], v[64:67]
	v_mfma_f32_16x16x32_bf16 v[118:121], v[186:189], v[202:205], v[118:121]
	v_mfma_f32_16x16x32_bf16 v[114:117], v[194:197], v[202:205], v[114:117]
	v_mfma_f32_16x16x32_bf16 v[102:105], v[186:189], v[210:213], v[102:105]
	v_mfma_f32_16x16x32_bf16 v[98:101], v[194:197], v[210:213], v[98:101]
	v_mfma_f32_16x16x32_bf16 v[84:87], v[186:189], v[218:221], v[84:87]
	v_mfma_f32_16x16x32_bf16 v[80:83], v[194:197], v[218:221], v[80:83]
	v_mfma_f32_16x16x32_bf16 v[68:71], v[186:189], v[226:229], v[68:71]
	v_mfma_f32_16x16x32_bf16 v[64:67], v[194:197], v[226:229], v[64:67]
	s_setprio 0
	s_barrier
	s_setprio 2
	s_add_i32 s54, s54, s36
	v_lshl_add_u64 v[154:155], s[26:27], 0, v[96:97]
	s_mov_b32 m0, s54
	ds_read_b128 v[198:201], v145 offset:16384
	ds_read_b128 v[202:205], v145 offset:17408
	ds_read_b128 v[206:209], v145 offset:18432
	ds_read_b128 v[210:213], v145 offset:19456
	ds_read_b128 v[214:217], v145 offset:20480
	ds_read_b128 v[218:221], v145 offset:21504
	ds_read_b128 v[222:225], v145 offset:22528
	ds_read_b128 v[226:229], v145 offset:23552
	global_load_lds_dwordx4 v[154:155], off
	s_add_i32 m0, s54, 0x2000
	s_add_u32 s54, s26, 0x40000
	v_lshl_add_u64 v[156:157], s[26:27], 0, v[130:131]
	s_addc_u32 s55, s27, 0
	s_add_i32 s56, s56, s36
	global_load_lds_dwordx4 v[156:157], off
	v_lshl_add_u64 v[158:159], s[54:55], 0, v[96:97]
	s_mov_b32 m0, s56
	v_lshl_add_u64 v[182:183], s[28:29], 0, v[132:133]
	global_load_lds_dwordx4 v[158:159], off
	v_lshl_add_u64 v[158:159], s[54:55], 0, v[130:131]
	s_add_i32 m0, s56, 0x2000
	s_nop 0
	global_load_lds_dwordx4 v[158:159], off
	v_lshl_add_u64 v[158:159], s[28:29], 0, v[134:135]
	s_mov_b32 m0, s37
	s_nop 0
	global_load_lds_dwordx4 v[158:159], off
	s_mov_b32 m0, s38
	s_nop 0
	global_load_lds_dwordx4 v[182:183], off
	s_waitcnt vmcnt(8) lgkmcnt(0)
	s_barrier
	s_setprio 1
	v_mfma_f32_16x16x32_bf16 v[60:63], v[146:149], v[198:201], v[60:63]
	v_mfma_f32_16x16x32_bf16 v[56:59], v[162:165], v[198:201], v[56:59]
	v_mfma_f32_16x16x32_bf16 v[44:47], v[146:149], v[206:209], v[44:47]
	v_mfma_f32_16x16x32_bf16 v[40:43], v[162:165], v[206:209], v[40:43]
	v_mfma_f32_16x16x32_bf16 v[28:31], v[146:149], v[214:217], v[28:31]
	v_mfma_f32_16x16x32_bf16 v[24:27], v[162:165], v[214:217], v[24:27]
	v_mfma_f32_16x16x32_bf16 v[12:15], v[146:149], v[222:225], v[12:15]
	v_mfma_f32_16x16x32_bf16 v[4:7], v[162:165], v[222:225], v[4:7]
	v_mfma_f32_16x16x32_bf16 v[60:63], v[150:153], v[202:205], v[60:63]
	v_mfma_f32_16x16x32_bf16 v[56:59], v[166:169], v[202:205], v[56:59]
	v_mfma_f32_16x16x32_bf16 v[44:47], v[150:153], v[210:213], v[44:47]
	v_mfma_f32_16x16x32_bf16 v[40:43], v[166:169], v[210:213], v[40:43]
	v_mfma_f32_16x16x32_bf16 v[28:31], v[150:153], v[218:221], v[28:31]
	v_mfma_f32_16x16x32_bf16 v[24:27], v[166:169], v[218:221], v[24:27]
	v_mfma_f32_16x16x32_bf16 v[12:15], v[150:153], v[226:229], v[12:15]
	v_mfma_f32_16x16x32_bf16 v[4:7], v[166:169], v[226:229], v[4:7]
	s_setprio 0
	s_setprio 1
	v_mfma_f32_16x16x32_bf16 v[52:55], v[170:173], v[198:201], v[52:55]
	v_mfma_f32_16x16x32_bf16 v[48:51], v[190:193], v[198:201], v[48:51]
	v_mfma_f32_16x16x32_bf16 v[36:39], v[170:173], v[206:209], v[36:39]
	v_mfma_f32_16x16x32_bf16 v[32:35], v[190:193], v[206:209], v[32:35]
	v_mfma_f32_16x16x32_bf16 v[20:23], v[170:173], v[214:217], v[20:23]
	v_mfma_f32_16x16x32_bf16 v[16:19], v[190:193], v[214:217], v[16:19]
	v_mfma_f32_16x16x32_bf16 v[8:11], v[170:173], v[222:225], v[8:11]
	v_mfma_f32_16x16x32_bf16 v[0:3], v[190:193], v[222:225], v[0:3]
	v_mfma_f32_16x16x32_bf16 v[52:55], v[186:189], v[202:205], v[52:55]
	v_mfma_f32_16x16x32_bf16 v[48:51], v[194:197], v[202:205], v[48:51]
	v_mfma_f32_16x16x32_bf16 v[36:39], v[186:189], v[210:213], v[36:39]
	v_mfma_f32_16x16x32_bf16 v[32:35], v[194:197], v[210:213], v[32:35]
	v_mfma_f32_16x16x32_bf16 v[20:23], v[186:189], v[218:221], v[20:23]
	v_mfma_f32_16x16x32_bf16 v[16:19], v[194:197], v[218:221], v[16:19]
	v_mfma_f32_16x16x32_bf16 v[8:11], v[186:189], v[226:229], v[8:11]
	v_mfma_f32_16x16x32_bf16 v[0:3], v[194:197], v[226:229], v[0:3]
	s_setprio 0
	s_barrier
	s_setprio 2
	s_add_i32 s54, 0, 0x18000
	s_add_i32 s55, 0, 0x1c000
	v_add_u32_e32 v166, s54, v141
	v_add_u32_e32 v184, s55, v141
	ds_read_b128 v[146:149], v166
	ds_read_b128 v[150:153], v166 offset:1024
	ds_read_b128 v[162:165], v166 offset:2048
	ds_read_b128 v[166:169], v166 offset:3072
	ds_read_b128 v[170:173], v184
	ds_read_b128 v[186:189], v184 offset:1024
	ds_read_b128 v[190:193], v184 offset:2048
	ds_read_b128 v[194:197], v184 offset:3072
	s_add_u32 s28, s28, 0x40000
	s_addc_u32 s29, s29, 0
	s_mov_b32 m0, s39
	v_lshl_add_u64 v[184:185], s[28:29], 0, v[134:135]
	ds_read_b128 v[198:201], v145 offset:32768
	ds_read_b128 v[202:205], v145 offset:33792
	ds_read_b128 v[206:209], v145 offset:34816
	ds_read_b128 v[210:213], v145 offset:35840
	ds_read_b128 v[214:217], v145 offset:36864
	ds_read_b128 v[218:221], v145 offset:37888
	ds_read_b128 v[222:225], v145 offset:38912
	ds_read_b128 v[226:229], v145 offset:39936
	global_load_lds_dwordx4 v[184:185], off
	v_lshl_add_u64 v[184:185], s[28:29], 0, v[132:133]
	s_mov_b32 m0, s40
	s_nop 0
	global_load_lds_dwordx4 v[184:185], off
	s_waitcnt vmcnt(8) lgkmcnt(0)
	s_barrier
	s_setprio 1
	v_mfma_f32_16x16x32_bf16 v[126:129], v[146:149], v[198:201], v[126:129]
	v_mfma_f32_16x16x32_bf16 v[122:125], v[162:165], v[198:201], v[122:125]
	v_mfma_f32_16x16x32_bf16 v[110:113], v[146:149], v[206:209], v[110:113]
	v_mfma_f32_16x16x32_bf16 v[106:109], v[162:165], v[206:209], v[106:109]
	v_mfma_f32_16x16x32_bf16 v[92:95], v[146:149], v[214:217], v[92:95]
	v_mfma_f32_16x16x32_bf16 v[88:91], v[162:165], v[214:217], v[88:91]
	v_mfma_f32_16x16x32_bf16 v[76:79], v[146:149], v[222:225], v[76:79]
	v_mfma_f32_16x16x32_bf16 v[72:75], v[162:165], v[222:225], v[72:75]
	v_mfma_f32_16x16x32_bf16 v[126:129], v[150:153], v[202:205], v[126:129]
	v_mfma_f32_16x16x32_bf16 v[122:125], v[166:169], v[202:205], v[122:125]
	v_mfma_f32_16x16x32_bf16 v[110:113], v[150:153], v[210:213], v[110:113]
	v_mfma_f32_16x16x32_bf16 v[106:109], v[166:169], v[210:213], v[106:109]
	v_mfma_f32_16x16x32_bf16 v[92:95], v[150:153], v[218:221], v[92:95]
	v_mfma_f32_16x16x32_bf16 v[88:91], v[166:169], v[218:221], v[88:91]
	v_mfma_f32_16x16x32_bf16 v[76:79], v[150:153], v[226:229], v[76:79]
	v_mfma_f32_16x16x32_bf16 v[72:75], v[166:169], v[226:229], v[72:75]
	s_setprio 0
	s_setprio 1
	v_mfma_f32_16x16x32_bf16 v[118:121], v[170:173], v[198:201], v[118:121]
	v_mfma_f32_16x16x32_bf16 v[114:117], v[190:193], v[198:201], v[114:117]
	v_mfma_f32_16x16x32_bf16 v[102:105], v[170:173], v[206:209], v[102:105]
	v_mfma_f32_16x16x32_bf16 v[98:101], v[190:193], v[206:209], v[98:101]
	v_mfma_f32_16x16x32_bf16 v[84:87], v[170:173], v[214:217], v[84:87]
	v_mfma_f32_16x16x32_bf16 v[80:83], v[190:193], v[214:217], v[80:83]
	v_mfma_f32_16x16x32_bf16 v[68:71], v[170:173], v[222:225], v[68:71]
	v_mfma_f32_16x16x32_bf16 v[64:67], v[190:193], v[222:225], v[64:67]
	v_mfma_f32_16x16x32_bf16 v[118:121], v[186:189], v[202:205], v[118:121]
	v_mfma_f32_16x16x32_bf16 v[114:117], v[194:197], v[202:205], v[114:117]
	v_mfma_f32_16x16x32_bf16 v[102:105], v[186:189], v[210:213], v[102:105]
	v_mfma_f32_16x16x32_bf16 v[98:101], v[194:197], v[210:213], v[98:101]
	v_mfma_f32_16x16x32_bf16 v[84:87], v[186:189], v[218:221], v[84:87]
	v_mfma_f32_16x16x32_bf16 v[80:83], v[194:197], v[218:221], v[80:83]
	v_mfma_f32_16x16x32_bf16 v[68:71], v[186:189], v[226:229], v[68:71]
	v_mfma_f32_16x16x32_bf16 v[64:67], v[194:197], v[226:229], v[64:67]
	s_setprio 0
	s_barrier
	s_setprio 2
	s_add_i32 s28, s54, s36
	v_lshl_add_u64 v[154:155], v[154:155], 0, s[16:17]
	s_mov_b32 m0, s28
	ds_read_b128 v[198:201], v145 offset:49152
	ds_read_b128 v[202:205], v145 offset:50176
	ds_read_b128 v[206:209], v145 offset:51200
	ds_read_b128 v[210:213], v145 offset:52224
	ds_read_b128 v[214:217], v145 offset:53248
	ds_read_b128 v[218:221], v145 offset:54272
	ds_read_b128 v[222:225], v145 offset:55296
	ds_read_b128 v[226:229], v145 offset:56320
	global_load_lds_dwordx4 v[154:155], off
	s_add_i32 m0, s28, 0x2000
	s_add_u32 s26, s26, 0x40080
	v_lshl_add_u64 v[154:155], v[156:157], 0, s[16:17]
	s_addc_u32 s27, s27, 0
	s_add_i32 s28, s55, s36
	global_load_lds_dwordx4 v[154:155], off
	v_lshl_add_u64 v[154:155], s[26:27], 0, v[96:97]
	s_mov_b32 m0, s28
	s_nop 0
	global_load_lds_dwordx4 v[154:155], off
	v_lshl_add_u64 v[154:155], s[26:27], 0, v[130:131]
	s_add_i32 m0, s28, 0x2000
	s_nop 0
	global_load_lds_dwordx4 v[154:155], off
	v_lshl_add_u64 v[154:155], v[158:159], 0, s[16:17]
	s_mov_b32 m0, s41
	s_nop 0
	global_load_lds_dwordx4 v[154:155], off
	v_lshl_add_u64 v[154:155], v[182:183], 0, s[16:17]
	s_mov_b32 m0, s42
	s_nop 0
	global_load_lds_dwordx4 v[154:155], off
	s_waitcnt vmcnt(8) lgkmcnt(0)
	s_barrier
	s_setprio 1
	v_mfma_f32_16x16x32_bf16 v[60:63], v[146:149], v[198:201], v[60:63]
	v_mfma_f32_16x16x32_bf16 v[56:59], v[162:165], v[198:201], v[56:59]
	v_mfma_f32_16x16x32_bf16 v[44:47], v[146:149], v[206:209], v[44:47]
	v_mfma_f32_16x16x32_bf16 v[40:43], v[162:165], v[206:209], v[40:43]
	v_mfma_f32_16x16x32_bf16 v[28:31], v[146:149], v[214:217], v[28:31]
	v_mfma_f32_16x16x32_bf16 v[24:27], v[162:165], v[214:217], v[24:27]
	v_mfma_f32_16x16x32_bf16 v[12:15], v[146:149], v[222:225], v[12:15]
	v_mfma_f32_16x16x32_bf16 v[4:7], v[162:165], v[222:225], v[4:7]
	v_mfma_f32_16x16x32_bf16 v[60:63], v[150:153], v[202:205], v[60:63]
	v_mfma_f32_16x16x32_bf16 v[56:59], v[166:169], v[202:205], v[56:59]
	v_mfma_f32_16x16x32_bf16 v[44:47], v[150:153], v[210:213], v[44:47]
	v_mfma_f32_16x16x32_bf16 v[40:43], v[166:169], v[210:213], v[40:43]
	v_mfma_f32_16x16x32_bf16 v[28:31], v[150:153], v[218:221], v[28:31]
	v_mfma_f32_16x16x32_bf16 v[24:27], v[166:169], v[218:221], v[24:27]
	v_mfma_f32_16x16x32_bf16 v[12:15], v[150:153], v[226:229], v[12:15]
	v_mfma_f32_16x16x32_bf16 v[4:7], v[166:169], v[226:229], v[4:7]
	s_setprio 0
	s_setprio 1
	v_mfma_f32_16x16x32_bf16 v[52:55], v[170:173], v[198:201], v[52:55]
	v_mfma_f32_16x16x32_bf16 v[48:51], v[190:193], v[198:201], v[48:51]
	v_mfma_f32_16x16x32_bf16 v[36:39], v[170:173], v[206:209], v[36:39]
	v_mfma_f32_16x16x32_bf16 v[32:35], v[190:193], v[206:209], v[32:35]
	v_mfma_f32_16x16x32_bf16 v[20:23], v[170:173], v[214:217], v[20:23]
	v_mfma_f32_16x16x32_bf16 v[16:19], v[190:193], v[214:217], v[16:19]
	v_mfma_f32_16x16x32_bf16 v[8:11], v[170:173], v[222:225], v[8:11]
	v_mfma_f32_16x16x32_bf16 v[0:3], v[190:193], v[222:225], v[0:3]
	v_mfma_f32_16x16x32_bf16 v[52:55], v[186:189], v[202:205], v[52:55]
	v_mfma_f32_16x16x32_bf16 v[48:51], v[194:197], v[202:205], v[48:51]
	v_mfma_f32_16x16x32_bf16 v[36:39], v[186:189], v[210:213], v[36:39]
	v_mfma_f32_16x16x32_bf16 v[32:35], v[194:197], v[210:213], v[32:35]
	v_mfma_f32_16x16x32_bf16 v[20:23], v[186:189], v[218:221], v[20:23]
	v_mfma_f32_16x16x32_bf16 v[16:19], v[194:197], v[218:221], v[16:19]
	v_mfma_f32_16x16x32_bf16 v[8:11], v[186:189], v[226:229], v[8:11]
	v_mfma_f32_16x16x32_bf16 v[0:3], v[194:197], v[226:229], v[0:3]
	s_setprio 0
	s_barrier
	s_setprio 2
	s_add_i32 s53, s53, 2
	s_add_u32 s14, s14, 0x100
	s_addc_u32 s15, s15, 0
	s_add_u32 s51, s51, 0x100
	s_addc_u32 s52, s52, 0
	s_cmp_gt_u32 s53, 13
	s_cbranch_scc0 .LBB0_271
	s_and_b64 vcc, exec, s[12:13]
	s_cbranch_vccz .LBB0_274
	s_barrier

.LBB0_361:
	s_add_u32 s34, s30, 0xfffc0080
	s_addc_u32 s35, s31, -1
	s_add_i32 s62, 0, 0x10000
	s_cmp_eq_u32 s61, 12
	s_cselect_b32 s37, s25, s35
	s_cselect_b32 s36, s57, s34
	v_add_u32_e32 v96, s62, v151
	s_cselect_b32 s35, s15, s60
	s_cselect_b32 s34, s58, s59
	s_add_i32 s64, 0, 0x14000
	ds_read_b128 v[164:167], v96
	ds_read_b128 v[168:171], v96 offset:1024
	ds_read_b128 v[186:189], v96 offset:2048
	ds_read_b128 v[190:193], v96 offset:3072
	v_add_u32_e32 v96, s64, v151
	ds_read_b128 v[194:197], v96
	ds_read_b128 v[198:201], v96 offset:1024
	ds_read_b128 v[202:205], v96 offset:2048
	ds_read_b128 v[206:209], v96 offset:3072
	v_lshl_add_u64 v[154:155], s[30:31], 0, v[146:147]
	s_add_i32 m0, s43, 0xc000
	ds_read_b128 v[210:213], v162
	ds_read_b128 v[214:217], v162 offset:1024
	ds_read_b128 v[218:221], v162 offset:2048
	ds_read_b128 v[222:225], v162 offset:3072
	ds_read_b128 v[226:229], v162 offset:4096
	ds_read_b128 v[230:233], v162 offset:5120
	ds_read_b128 v[242:245], v162 offset:6144
	ds_read_b128 v[246:249], v162 offset:7168
	global_load_lds_dwordx4 v[154:155], off
	v_lshl_add_u64 v[154:155], s[30:31], 0, v[148:149]
	s_add_i32 m0, s43, 0xe000
	s_nop 0
	global_load_lds_dwordx4 v[154:155], off
	s_waitcnt vmcnt(8) lgkmcnt(0)
	s_barrier
	s_setprio 1
	v_mfma_f32_16x16x32_bf16 v[126:129], v[164:167], v[210:213], v[126:129]
	v_mfma_f32_16x16x32_bf16 v[122:125], v[186:189], v[210:213], v[122:125]
	v_mfma_f32_16x16x32_bf16 v[118:121], v[164:167], v[218:221], v[118:121]
	v_mfma_f32_16x16x32_bf16 v[114:117], v[186:189], v[218:221], v[114:117]
	v_mfma_f32_16x16x32_bf16 v[110:113], v[164:167], v[226:229], v[110:113]
	v_mfma_f32_16x16x32_bf16 v[106:109], v[186:189], v[226:229], v[106:109]
	v_mfma_f32_16x16x32_bf16 v[102:105], v[164:167], v[242:245], v[102:105]
	v_mfma_f32_16x16x32_bf16 v[98:101], v[186:189], v[242:245], v[98:101]
	v_mfma_f32_16x16x32_bf16 v[126:129], v[168:171], v[214:217], v[126:129]
	v_mfma_f32_16x16x32_bf16 v[122:125], v[190:193], v[214:217], v[122:125]
	v_mfma_f32_16x16x32_bf16 v[118:121], v[168:171], v[222:225], v[118:121]
	v_mfma_f32_16x16x32_bf16 v[114:117], v[190:193], v[222:225], v[114:117]
	v_mfma_f32_16x16x32_bf16 v[110:113], v[168:171], v[230:233], v[110:113]
	v_mfma_f32_16x16x32_bf16 v[106:109], v[190:193], v[230:233], v[106:109]
	v_mfma_f32_16x16x32_bf16 v[102:105], v[168:171], v[246:249], v[102:105]
	v_mfma_f32_16x16x32_bf16 v[98:101], v[190:193], v[246:249], v[98:101]
	s_setprio 0
	s_setprio 1
	v_mfma_f32_16x16x32_bf16 v[76:79], v[194:197], v[210:213], v[76:79]
	v_mfma_f32_16x16x32_bf16 v[64:67], v[202:205], v[210:213], v[64:67]
	v_mfma_f32_16x16x32_bf16 v[60:63], v[194:197], v[218:221], v[60:63]
	v_mfma_f32_16x16x32_bf16 v[52:55], v[202:205], v[218:221], v[52:55]
	v_mfma_f32_16x16x32_bf16 v[44:47], v[194:197], v[226:229], v[44:47]
	v_mfma_f32_16x16x32_bf16 v[40:43], v[202:205], v[226:229], v[40:43]
	v_mfma_f32_16x16x32_bf16 v[36:39], v[194:197], v[242:245], v[36:39]
	v_mfma_f32_16x16x32_bf16 v[32:35], v[202:205], v[242:245], v[32:35]
	v_mfma_f32_16x16x32_bf16 v[76:79], v[198:201], v[214:217], v[76:79]
	v_mfma_f32_16x16x32_bf16 v[64:67], v[206:209], v[214:217], v[64:67]
	v_mfma_f32_16x16x32_bf16 v[60:63], v[198:201], v[222:225], v[60:63]
	v_mfma_f32_16x16x32_bf16 v[52:55], v[206:209], v[222:225], v[52:55]
	v_mfma_f32_16x16x32_bf16 v[44:47], v[198:201], v[230:233], v[44:47]
	v_mfma_f32_16x16x32_bf16 v[40:43], v[206:209], v[230:233], v[40:43]
	v_mfma_f32_16x16x32_bf16 v[36:39], v[198:201], v[246:249], v[36:39]
	v_mfma_f32_16x16x32_bf16 v[32:35], v[206:209], v[246:249], v[32:35]
	s_setprio 0
	s_barrier
	s_setprio 2
	s_add_i32 s62, s62, s40
	v_lshl_add_u64 v[154:155], s[34:35], 0, v[134:135]
	s_mov_b32 m0, s62
	ds_read_b128 v[210:213], v162 offset:16384
	ds_read_b128 v[214:217], v162 offset:17408
	ds_read_b128 v[218:221], v162 offset:18432
	ds_read_b128 v[222:225], v162 offset:19456
	ds_read_b128 v[226:229], v162 offset:20480
	ds_read_b128 v[230:233], v162 offset:21504
	ds_read_b128 v[242:245], v162 offset:22528
	ds_read_b128 v[246:249], v162 offset:23552
	global_load_lds_dwordx4 v[154:155], off
	s_add_i32 m0, s62, 0x2000
	s_add_u32 s62, s34, 0x40000
	v_lshl_add_u64 v[156:157], s[34:35], 0, v[130:131]
	s_addc_u32 s63, s35, 0
	s_add_i32 s64, s64, s40
	global_load_lds_dwordx4 v[156:157], off
	v_lshl_add_u64 v[158:159], s[62:63], 0, v[134:135]
	s_mov_b32 m0, s64
	v_lshl_add_u64 v[172:173], s[36:37], 0, v[132:133]
	global_load_lds_dwordx4 v[158:159], off
	v_lshl_add_u64 v[158:159], s[62:63], 0, v[130:131]
	s_add_i32 m0, s64, 0x2000
	s_nop 0
	global_load_lds_dwordx4 v[158:159], off
	v_lshl_add_u64 v[158:159], s[36:37], 0, v[136:137]
	s_mov_b32 m0, s43
	s_nop 0
	global_load_lds_dwordx4 v[158:159], off
	s_mov_b32 m0, s44
	s_nop 0
	global_load_lds_dwordx4 v[172:173], off
	s_waitcnt vmcnt(8) lgkmcnt(0)
	s_barrier
	s_setprio 1
	v_mfma_f32_16x16x32_bf16 v[92:95], v[164:167], v[210:213], v[92:95]
	v_mfma_f32_16x16x32_bf16 v[88:91], v[186:189], v[210:213], v[88:91]
	v_mfma_f32_16x16x32_bf16 v[84:87], v[164:167], v[218:221], v[84:87]
	v_mfma_f32_16x16x32_bf16 v[80:83], v[186:189], v[218:221], v[80:83]
	v_mfma_f32_16x16x32_bf16 v[72:75], v[164:167], v[226:229], v[72:75]
	v_mfma_f32_16x16x32_bf16 v[68:71], v[186:189], v[226:229], v[68:71]
	v_mfma_f32_16x16x32_bf16 v[56:59], v[164:167], v[242:245], v[56:59]
	v_mfma_f32_16x16x32_bf16 v[48:51], v[186:189], v[242:245], v[48:51]
	v_mfma_f32_16x16x32_bf16 v[92:95], v[168:171], v[214:217], v[92:95]
	v_mfma_f32_16x16x32_bf16 v[88:91], v[190:193], v[214:217], v[88:91]
	v_mfma_f32_16x16x32_bf16 v[84:87], v[168:171], v[222:225], v[84:87]
	v_mfma_f32_16x16x32_bf16 v[80:83], v[190:193], v[222:225], v[80:83]
	v_mfma_f32_16x16x32_bf16 v[72:75], v[168:171], v[230:233], v[72:75]
	v_mfma_f32_16x16x32_bf16 v[68:71], v[190:193], v[230:233], v[68:71]
	v_mfma_f32_16x16x32_bf16 v[56:59], v[168:171], v[246:249], v[56:59]
	v_mfma_f32_16x16x32_bf16 v[48:51], v[190:193], v[246:249], v[48:51]
	s_setprio 0
	s_setprio 1
	v_mfma_f32_16x16x32_bf16 v[28:31], v[194:197], v[210:213], v[28:31]
	v_mfma_f32_16x16x32_bf16 v[24:27], v[202:205], v[210:213], v[24:27]
	v_mfma_f32_16x16x32_bf16 v[20:23], v[194:197], v[218:221], v[20:23]
	v_mfma_f32_16x16x32_bf16 v[16:19], v[202:205], v[218:221], v[16:19]
	v_mfma_f32_16x16x32_bf16 v[12:15], v[194:197], v[226:229], v[12:15]
	v_mfma_f32_16x16x32_bf16 v[8:11], v[202:205], v[226:229], v[8:11]
	v_mfma_f32_16x16x32_bf16 v[4:7], v[194:197], v[242:245], v[4:7]
	v_mfma_f32_16x16x32_bf16 v[0:3], v[202:205], v[242:245], v[0:3]
	v_mfma_f32_16x16x32_bf16 v[28:31], v[198:201], v[214:217], v[28:31]
	v_mfma_f32_16x16x32_bf16 v[24:27], v[206:209], v[214:217], v[24:27]
	v_mfma_f32_16x16x32_bf16 v[20:23], v[198:201], v[222:225], v[20:23]
	v_mfma_f32_16x16x32_bf16 v[16:19], v[206:209], v[222:225], v[16:19]
	v_mfma_f32_16x16x32_bf16 v[12:15], v[198:201], v[230:233], v[12:15]
	v_mfma_f32_16x16x32_bf16 v[8:11], v[206:209], v[230:233], v[8:11]
	v_mfma_f32_16x16x32_bf16 v[4:7], v[198:201], v[246:249], v[4:7]
	v_mfma_f32_16x16x32_bf16 v[0:3], v[206:209], v[246:249], v[0:3]
	s_setprio 0
	s_barrier
	s_setprio 2
	s_add_i32 s62, 0, 0x18000
	v_add_u32_e32 v96, s62, v151
	s_add_i32 s63, 0, 0x1c000
	ds_read_b128 v[164:167], v96
	ds_read_b128 v[168:171], v96 offset:1024
	ds_read_b128 v[186:189], v96 offset:2048
	ds_read_b128 v[190:193], v96 offset:3072
	v_add_u32_e32 v96, s63, v151
	ds_read_b128 v[194:197], v96
	ds_read_b128 v[198:201], v96 offset:1024
	ds_read_b128 v[202:205], v96 offset:2048
	ds_read_b128 v[206:209], v96 offset:3072
	s_add_u32 s36, s36, 0x40000
	s_addc_u32 s37, s37, 0
	s_mov_b32 m0, s45
	v_lshl_add_u64 v[182:183], s[36:37], 0, v[136:137]
	ds_read_b128 v[210:213], v162 offset:32768
	ds_read_b128 v[214:217], v162 offset:33792
	ds_read_b128 v[218:221], v162 offset:34816
	ds_read_b128 v[222:225], v162 offset:35840
	ds_read_b128 v[226:229], v162 offset:36864
	ds_read_b128 v[230:233], v162 offset:37888
	ds_read_b128 v[242:245], v162 offset:38912
	ds_read_b128 v[246:249], v162 offset:39936
	global_load_lds_dwordx4 v[182:183], off
	v_lshl_add_u64 v[182:183], s[36:37], 0, v[132:133]
	s_mov_b32 m0, s46
	s_nop 0
	global_load_lds_dwordx4 v[182:183], off
	s_waitcnt vmcnt(8) lgkmcnt(0)
	s_barrier
	s_setprio 1
	v_mfma_f32_16x16x32_bf16 v[126:129], v[164:167], v[210:213], v[126:129]
	v_mfma_f32_16x16x32_bf16 v[122:125], v[186:189], v[210:213], v[122:125]
	v_mfma_f32_16x16x32_bf16 v[118:121], v[164:167], v[218:221], v[118:121]
	v_mfma_f32_16x16x32_bf16 v[114:117], v[186:189], v[218:221], v[114:117]
	v_mfma_f32_16x16x32_bf16 v[110:113], v[164:167], v[226:229], v[110:113]
	v_mfma_f32_16x16x32_bf16 v[106:109], v[186:189], v[226:229], v[106:109]
	v_mfma_f32_16x16x32_bf16 v[102:105], v[164:167], v[242:245], v[102:105]
	v_mfma_f32_16x16x32_bf16 v[98:101], v[186:189], v[242:245], v[98:101]
	v_mfma_f32_16x16x32_bf16 v[126:129], v[168:171], v[214:217], v[126:129]
	v_mfma_f32_16x16x32_bf16 v[122:125], v[190:193], v[214:217], v[122:125]
	v_mfma_f32_16x16x32_bf16 v[118:121], v[168:171], v[222:225], v[118:121]
	v_mfma_f32_16x16x32_bf16 v[114:117], v[190:193], v[222:225], v[114:117]
	v_mfma_f32_16x16x32_bf16 v[110:113], v[168:171], v[230:233], v[110:113]
	v_mfma_f32_16x16x32_bf16 v[106:109], v[190:193], v[230:233], v[106:109]
	v_mfma_f32_16x16x32_bf16 v[102:105], v[168:171], v[246:249], v[102:105]
	v_mfma_f32_16x16x32_bf16 v[98:101], v[190:193], v[246:249], v[98:101]
	s_setprio 0
	s_setprio 1
	v_mfma_f32_16x16x32_bf16 v[76:79], v[194:197], v[210:213], v[76:79]
	v_mfma_f32_16x16x32_bf16 v[64:67], v[202:205], v[210:213], v[64:67]
	v_mfma_f32_16x16x32_bf16 v[60:63], v[194:197], v[218:221], v[60:63]
	v_mfma_f32_16x16x32_bf16 v[52:55], v[202:205], v[218:221], v[52:55]
	v_mfma_f32_16x16x32_bf16 v[44:47], v[194:197], v[226:229], v[44:47]
	v_mfma_f32_16x16x32_bf16 v[40:43], v[202:205], v[226:229], v[40:43]
	v_mfma_f32_16x16x32_bf16 v[36:39], v[194:197], v[242:245], v[36:39]
	v_mfma_f32_16x16x32_bf16 v[32:35], v[202:205], v[242:245], v[32:35]
	v_mfma_f32_16x16x32_bf16 v[76:79], v[198:201], v[214:217], v[76:79]
	v_mfma_f32_16x16x32_bf16 v[64:67], v[206:209], v[214:217], v[64:67]
	v_mfma_f32_16x16x32_bf16 v[60:63], v[198:201], v[222:225], v[60:63]
	v_mfma_f32_16x16x32_bf16 v[52:55], v[206:209], v[222:225], v[52:55]
	v_mfma_f32_16x16x32_bf16 v[44:47], v[198:201], v[230:233], v[44:47]
	v_mfma_f32_16x16x32_bf16 v[40:43], v[206:209], v[230:233], v[40:43]
	v_mfma_f32_16x16x32_bf16 v[36:39], v[198:201], v[246:249], v[36:39]
	v_mfma_f32_16x16x32_bf16 v[32:35], v[206:209], v[246:249], v[32:35]
	s_setprio 0
	s_barrier
	s_setprio 2
	s_add_i32 s36, s62, s40
	v_lshl_add_u64 v[154:155], v[154:155], 0, s[16:17]
	s_mov_b32 m0, s36
	ds_read_b128 v[210:213], v162 offset:49152
	ds_read_b128 v[214:217], v162 offset:50176
	ds_read_b128 v[218:221], v162 offset:51200
	ds_read_b128 v[222:225], v162 offset:52224
	ds_read_b128 v[226:229], v162 offset:53248
	ds_read_b128 v[230:233], v162 offset:54272
	ds_read_b128 v[242:245], v162 offset:55296
	ds_read_b128 v[246:249], v162 offset:56320
	global_load_lds_dwordx4 v[154:155], off
	s_add_i32 m0, s36, 0x2000
	s_add_u32 s34, s34, 0x40080
	v_lshl_add_u64 v[154:155], v[156:157], 0, s[16:17]
	s_addc_u32 s35, s35, 0
	s_add_i32 s36, s63, s40
	global_load_lds_dwordx4 v[154:155], off
	v_lshl_add_u64 v[154:155], s[34:35], 0, v[134:135]
	s_mov_b32 m0, s36
	s_nop 0
	global_load_lds_dwordx4 v[154:155], off
	v_lshl_add_u64 v[154:155], s[34:35], 0, v[130:131]
	s_add_i32 m0, s36, 0x2000
	s_nop 0
	global_load_lds_dwordx4 v[154:155], off
	v_lshl_add_u64 v[154:155], v[158:159], 0, s[16:17]
	s_mov_b32 m0, s50
	s_nop 0
	global_load_lds_dwordx4 v[154:155], off
	v_lshl_add_u64 v[154:155], v[172:173], 0, s[16:17]
	s_mov_b32 m0, s51
	s_nop 0
	global_load_lds_dwordx4 v[154:155], off
	s_waitcnt vmcnt(8) lgkmcnt(0)
	s_barrier
	s_setprio 1
	v_mfma_f32_16x16x32_bf16 v[92:95], v[164:167], v[210:213], v[92:95]
	v_mfma_f32_16x16x32_bf16 v[88:91], v[186:189], v[210:213], v[88:91]
	v_mfma_f32_16x16x32_bf16 v[84:87], v[164:167], v[218:221], v[84:87]
	v_mfma_f32_16x16x32_bf16 v[80:83], v[186:189], v[218:221], v[80:83]
	v_mfma_f32_16x16x32_bf16 v[72:75], v[164:167], v[226:229], v[72:75]
	v_mfma_f32_16x16x32_bf16 v[68:71], v[186:189], v[226:229], v[68:71]
	v_mfma_f32_16x16x32_bf16 v[56:59], v[164:167], v[242:245], v[56:59]
	v_mfma_f32_16x16x32_bf16 v[48:51], v[186:189], v[242:245], v[48:51]
	v_mfma_f32_16x16x32_bf16 v[92:95], v[168:171], v[214:217], v[92:95]
	v_mfma_f32_16x16x32_bf16 v[88:91], v[190:193], v[214:217], v[88:91]
	v_mfma_f32_16x16x32_bf16 v[84:87], v[168:171], v[222:225], v[84:87]
	v_mfma_f32_16x16x32_bf16 v[80:83], v[190:193], v[222:225], v[80:83]
	v_mfma_f32_16x16x32_bf16 v[72:75], v[168:171], v[230:233], v[72:75]
	v_mfma_f32_16x16x32_bf16 v[68:71], v[190:193], v[230:233], v[68:71]
	v_mfma_f32_16x16x32_bf16 v[56:59], v[168:171], v[246:249], v[56:59]
	v_mfma_f32_16x16x32_bf16 v[48:51], v[190:193], v[246:249], v[48:51]
	s_setprio 0
	s_setprio 1
	v_mfma_f32_16x16x32_bf16 v[28:31], v[194:197], v[210:213], v[28:31]
	v_mfma_f32_16x16x32_bf16 v[24:27], v[202:205], v[210:213], v[24:27]
	v_mfma_f32_16x16x32_bf16 v[20:23], v[194:197], v[218:221], v[20:23]
	v_mfma_f32_16x16x32_bf16 v[16:19], v[202:205], v[218:221], v[16:19]
	v_mfma_f32_16x16x32_bf16 v[12:15], v[194:197], v[226:229], v[12:15]
	v_mfma_f32_16x16x32_bf16 v[8:11], v[202:205], v[226:229], v[8:11]
	v_mfma_f32_16x16x32_bf16 v[4:7], v[194:197], v[242:245], v[4:7]
	v_mfma_f32_16x16x32_bf16 v[0:3], v[202:205], v[242:245], v[0:3]
	v_mfma_f32_16x16x32_bf16 v[28:31], v[198:201], v[214:217], v[28:31]
	v_mfma_f32_16x16x32_bf16 v[24:27], v[206:209], v[214:217], v[24:27]
	v_mfma_f32_16x16x32_bf16 v[20:23], v[198:201], v[222:225], v[20:23]
	v_mfma_f32_16x16x32_bf16 v[16:19], v[206:209], v[222:225], v[16:19]
	v_mfma_f32_16x16x32_bf16 v[12:15], v[198:201], v[230:233], v[12:15]
	v_mfma_f32_16x16x32_bf16 v[8:11], v[206:209], v[230:233], v[8:11]
	v_mfma_f32_16x16x32_bf16 v[4:7], v[198:201], v[246:249], v[4:7]
	v_mfma_f32_16x16x32_bf16 v[0:3], v[206:209], v[246:249], v[0:3]
	s_setprio 0
	s_barrier
	s_setprio 2
	s_add_i32 s61, s61, 2
	s_add_u32 s30, s30, 0x100
	s_addc_u32 s31, s31, 0
	s_add_u32 s59, s59, 0x100
	s_addc_u32 s60, s60, 0
	s_cmp_gt_u32 s61, 13
	s_cbranch_scc0 .LBB0_361
	s_and_b64 vcc, exec, s[20:21]
	s_cbranch_vccz .LBB0_364
	s_barrier

.LBB0_393:
	s_add_u32 s26, s14, 0xfffc0080
	s_addc_u32 s27, s15, -1
	s_add_i32 s57, 0, 0x10000
	s_cmp_eq_u32 s56, 12
	s_cselect_b32 s29, s19, s27
	s_cselect_b32 s28, s52, s26
	v_add_u32_e32 v151, s57, v141
	s_cselect_b32 s27, s5, s55
	s_cselect_b32 s26, s53, s54
	s_add_i32 s60, 0, 0x14000
	ds_read_b128 v[162:165], v151
	ds_read_b128 v[166:169], v151 offset:1024
	ds_read_b128 v[170:173], v151 offset:2048
	ds_read_b128 v[186:189], v151 offset:3072
	v_add_u32_e32 v151, s60, v141
	ds_read_b128 v[190:193], v151
	ds_read_b128 v[194:197], v151 offset:1024
	ds_read_b128 v[198:201], v151 offset:2048
	ds_read_b128 v[202:205], v151 offset:3072
	v_lshl_add_u64 v[152:153], s[14:15], 0, v[146:147]
	s_add_i32 m0, s39, 0xc000
	ds_read_b128 v[206:209], v150
	ds_read_b128 v[210:213], v150 offset:1024
	ds_read_b128 v[214:217], v150 offset:2048
	ds_read_b128 v[218:221], v150 offset:3072
	ds_read_b128 v[222:225], v150 offset:4096
	ds_read_b128 v[226:229], v150 offset:5120
	ds_read_b128 v[230:233], v150 offset:6144
	ds_read_b128 v[242:245], v150 offset:7168
	global_load_lds_dwordx4 v[152:153], off
	v_lshl_add_u64 v[152:153], s[14:15], 0, v[148:149]
	s_add_i32 m0, s39, 0xe000
	s_nop 0
	global_load_lds_dwordx4 v[152:153], off
	s_waitcnt vmcnt(8) lgkmcnt(0)
	s_barrier
	s_setprio 1
	v_mfma_f32_16x16x32_bf16 v[126:129], v[162:165], v[206:209], v[126:129]
	v_mfma_f32_16x16x32_bf16 v[122:125], v[170:173], v[206:209], v[122:125]
	v_mfma_f32_16x16x32_bf16 v[118:121], v[162:165], v[214:217], v[118:121]
	v_mfma_f32_16x16x32_bf16 v[114:117], v[170:173], v[214:217], v[114:117]
	v_mfma_f32_16x16x32_bf16 v[110:113], v[162:165], v[222:225], v[110:113]
	v_mfma_f32_16x16x32_bf16 v[106:109], v[170:173], v[222:225], v[106:109]
	v_mfma_f32_16x16x32_bf16 v[102:105], v[162:165], v[230:233], v[102:105]
	v_mfma_f32_16x16x32_bf16 v[98:101], v[170:173], v[230:233], v[98:101]
	v_mfma_f32_16x16x32_bf16 v[126:129], v[166:169], v[210:213], v[126:129]
	v_mfma_f32_16x16x32_bf16 v[122:125], v[186:189], v[210:213], v[122:125]
	v_mfma_f32_16x16x32_bf16 v[118:121], v[166:169], v[218:221], v[118:121]
	v_mfma_f32_16x16x32_bf16 v[114:117], v[186:189], v[218:221], v[114:117]
	v_mfma_f32_16x16x32_bf16 v[110:113], v[166:169], v[226:229], v[110:113]
	v_mfma_f32_16x16x32_bf16 v[106:109], v[186:189], v[226:229], v[106:109]
	v_mfma_f32_16x16x32_bf16 v[102:105], v[166:169], v[242:245], v[102:105]
	v_mfma_f32_16x16x32_bf16 v[98:101], v[186:189], v[242:245], v[98:101]
	s_setprio 0
	s_setprio 1
	v_mfma_f32_16x16x32_bf16 v[68:71], v[190:193], v[206:209], v[68:71]
	v_mfma_f32_16x16x32_bf16 v[64:67], v[198:201], v[206:209], v[64:67]
	v_mfma_f32_16x16x32_bf16 v[52:55], v[190:193], v[214:217], v[52:55]
	v_mfma_f32_16x16x32_bf16 v[48:51], v[198:201], v[214:217], v[48:51]
	v_mfma_f32_16x16x32_bf16 v[44:47], v[190:193], v[222:225], v[44:47]
	v_mfma_f32_16x16x32_bf16 v[40:43], v[198:201], v[222:225], v[40:43]
	v_mfma_f32_16x16x32_bf16 v[36:39], v[190:193], v[230:233], v[36:39]
	v_mfma_f32_16x16x32_bf16 v[32:35], v[198:201], v[230:233], v[32:35]
	v_mfma_f32_16x16x32_bf16 v[68:71], v[194:197], v[210:213], v[68:71]
	v_mfma_f32_16x16x32_bf16 v[64:67], v[202:205], v[210:213], v[64:67]
	v_mfma_f32_16x16x32_bf16 v[52:55], v[194:197], v[218:221], v[52:55]
	v_mfma_f32_16x16x32_bf16 v[48:51], v[202:205], v[218:221], v[48:51]
	v_mfma_f32_16x16x32_bf16 v[44:47], v[194:197], v[226:229], v[44:47]
	v_mfma_f32_16x16x32_bf16 v[40:43], v[202:205], v[226:229], v[40:43]
	v_mfma_f32_16x16x32_bf16 v[36:39], v[194:197], v[242:245], v[36:39]
	v_mfma_f32_16x16x32_bf16 v[32:35], v[202:205], v[242:245], v[32:35]
	s_setprio 0
	s_barrier
	s_setprio 2
	s_add_i32 s57, s57, s36
	v_lshl_add_u64 v[152:153], s[26:27], 0, v[96:97]
	s_mov_b32 m0, s57
	ds_read_b128 v[206:209], v150 offset:16384
	ds_read_b128 v[210:213], v150 offset:17408
	ds_read_b128 v[214:217], v150 offset:18432
	ds_read_b128 v[218:221], v150 offset:19456
	ds_read_b128 v[222:225], v150 offset:20480
	ds_read_b128 v[226:229], v150 offset:21504
	ds_read_b128 v[230:233], v150 offset:22528
	ds_read_b128 v[242:245], v150 offset:23552
	global_load_lds_dwordx4 v[152:153], off
	s_add_i32 m0, s57, 0x2000
	s_add_u32 s58, s26, 0x40000
	v_lshl_add_u64 v[154:155], s[26:27], 0, v[130:131]
	s_addc_u32 s59, s27, 0
	s_add_i32 s57, s60, s36
	global_load_lds_dwordx4 v[154:155], off
	v_lshl_add_u64 v[156:157], s[58:59], 0, v[96:97]
	s_mov_b32 m0, s57
	v_lshl_add_u64 v[158:159], s[28:29], 0, v[132:133]
	global_load_lds_dwordx4 v[156:157], off
	v_lshl_add_u64 v[156:157], s[58:59], 0, v[130:131]
	s_add_i32 m0, s57, 0x2000
	s_nop 0
	global_load_lds_dwordx4 v[156:157], off
	v_lshl_add_u64 v[156:157], s[28:29], 0, v[134:135]
	s_mov_b32 m0, s39
	s_nop 0
	global_load_lds_dwordx4 v[156:157], off
	s_mov_b32 m0, s40
	s_nop 0
	global_load_lds_dwordx4 v[158:159], off
	s_waitcnt vmcnt(8) lgkmcnt(0)
	s_barrier
	s_setprio 1
	v_mfma_f32_16x16x32_bf16 v[92:95], v[162:165], v[206:209], v[92:95]
	v_mfma_f32_16x16x32_bf16 v[88:91], v[170:173], v[206:209], v[88:91]
	v_mfma_f32_16x16x32_bf16 v[84:87], v[162:165], v[214:217], v[84:87]
	v_mfma_f32_16x16x32_bf16 v[80:83], v[170:173], v[214:217], v[80:83]
	v_mfma_f32_16x16x32_bf16 v[76:79], v[162:165], v[222:225], v[76:79]
	v_mfma_f32_16x16x32_bf16 v[72:75], v[170:173], v[222:225], v[72:75]
	v_mfma_f32_16x16x32_bf16 v[60:63], v[162:165], v[230:233], v[60:63]
	v_mfma_f32_16x16x32_bf16 v[56:59], v[170:173], v[230:233], v[56:59]
	v_mfma_f32_16x16x32_bf16 v[92:95], v[166:169], v[210:213], v[92:95]
	v_mfma_f32_16x16x32_bf16 v[88:91], v[186:189], v[210:213], v[88:91]
	v_mfma_f32_16x16x32_bf16 v[84:87], v[166:169], v[218:221], v[84:87]
	v_mfma_f32_16x16x32_bf16 v[80:83], v[186:189], v[218:221], v[80:83]
	v_mfma_f32_16x16x32_bf16 v[76:79], v[166:169], v[226:229], v[76:79]
	v_mfma_f32_16x16x32_bf16 v[72:75], v[186:189], v[226:229], v[72:75]
	v_mfma_f32_16x16x32_bf16 v[60:63], v[166:169], v[242:245], v[60:63]
	v_mfma_f32_16x16x32_bf16 v[56:59], v[186:189], v[242:245], v[56:59]
	s_setprio 0
	s_setprio 1
	v_mfma_f32_16x16x32_bf16 v[28:31], v[190:193], v[206:209], v[28:31]
	v_mfma_f32_16x16x32_bf16 v[24:27], v[198:201], v[206:209], v[24:27]
	v_mfma_f32_16x16x32_bf16 v[20:23], v[190:193], v[214:217], v[20:23]
	v_mfma_f32_16x16x32_bf16 v[16:19], v[198:201], v[214:217], v[16:19]
	v_mfma_f32_16x16x32_bf16 v[12:15], v[190:193], v[222:225], v[12:15]
	v_mfma_f32_16x16x32_bf16 v[8:11], v[198:201], v[222:225], v[8:11]
	v_mfma_f32_16x16x32_bf16 v[4:7], v[190:193], v[230:233], v[4:7]
	v_mfma_f32_16x16x32_bf16 v[0:3], v[198:201], v[230:233], v[0:3]
	v_mfma_f32_16x16x32_bf16 v[28:31], v[194:197], v[210:213], v[28:31]
	v_mfma_f32_16x16x32_bf16 v[24:27], v[202:205], v[210:213], v[24:27]
	v_mfma_f32_16x16x32_bf16 v[20:23], v[194:197], v[218:221], v[20:23]
	v_mfma_f32_16x16x32_bf16 v[16:19], v[202:205], v[218:221], v[16:19]
	v_mfma_f32_16x16x32_bf16 v[12:15], v[194:197], v[226:229], v[12:15]
	v_mfma_f32_16x16x32_bf16 v[8:11], v[202:205], v[226:229], v[8:11]
	v_mfma_f32_16x16x32_bf16 v[4:7], v[194:197], v[242:245], v[4:7]
	v_mfma_f32_16x16x32_bf16 v[0:3], v[202:205], v[242:245], v[0:3]
	s_setprio 0
	s_barrier
	s_setprio 2
	s_add_i32 s57, 0, 0x18000
	v_add_u32_e32 v151, s57, v141
	s_add_i32 s58, 0, 0x1c000
	ds_read_b128 v[162:165], v151
	ds_read_b128 v[166:169], v151 offset:1024
	ds_read_b128 v[170:173], v151 offset:2048
	ds_read_b128 v[186:189], v151 offset:3072
	v_add_u32_e32 v151, s58, v141
	ds_read_b128 v[190:193], v151
	ds_read_b128 v[194:197], v151 offset:1024
	ds_read_b128 v[198:201], v151 offset:2048
	ds_read_b128 v[202:205], v151 offset:3072
	s_add_u32 s28, s28, 0x40000
	s_addc_u32 s29, s29, 0
	s_mov_b32 m0, s41
	v_lshl_add_u64 v[182:183], s[28:29], 0, v[134:135]
	ds_read_b128 v[206:209], v150 offset:32768
	ds_read_b128 v[210:213], v150 offset:33792
	ds_read_b128 v[214:217], v150 offset:34816
	ds_read_b128 v[218:221], v150 offset:35840
	ds_read_b128 v[222:225], v150 offset:36864
	ds_read_b128 v[226:229], v150 offset:37888
	ds_read_b128 v[230:233], v150 offset:38912
	ds_read_b128 v[242:245], v150 offset:39936
	global_load_lds_dwordx4 v[182:183], off
	v_lshl_add_u64 v[182:183], s[28:29], 0, v[132:133]
	s_mov_b32 m0, s42
	s_nop 0
	global_load_lds_dwordx4 v[182:183], off
	s_waitcnt vmcnt(8) lgkmcnt(0)
	s_barrier
	s_setprio 1
	v_mfma_f32_16x16x32_bf16 v[126:129], v[162:165], v[206:209], v[126:129]
	v_mfma_f32_16x16x32_bf16 v[122:125], v[170:173], v[206:209], v[122:125]
	v_mfma_f32_16x16x32_bf16 v[118:121], v[162:165], v[214:217], v[118:121]
	v_mfma_f32_16x16x32_bf16 v[114:117], v[170:173], v[214:217], v[114:117]
	v_mfma_f32_16x16x32_bf16 v[110:113], v[162:165], v[222:225], v[110:113]
	v_mfma_f32_16x16x32_bf16 v[106:109], v[170:173], v[222:225], v[106:109]
	v_mfma_f32_16x16x32_bf16 v[102:105], v[162:165], v[230:233], v[102:105]
	v_mfma_f32_16x16x32_bf16 v[98:101], v[170:173], v[230:233], v[98:101]
	v_mfma_f32_16x16x32_bf16 v[126:129], v[166:169], v[210:213], v[126:129]
	v_mfma_f32_16x16x32_bf16 v[122:125], v[186:189], v[210:213], v[122:125]
	v_mfma_f32_16x16x32_bf16 v[118:121], v[166:169], v[218:221], v[118:121]
	v_mfma_f32_16x16x32_bf16 v[114:117], v[186:189], v[218:221], v[114:117]
	v_mfma_f32_16x16x32_bf16 v[110:113], v[166:169], v[226:229], v[110:113]
	v_mfma_f32_16x16x32_bf16 v[106:109], v[186:189], v[226:229], v[106:109]
	v_mfma_f32_16x16x32_bf16 v[102:105], v[166:169], v[242:245], v[102:105]
	v_mfma_f32_16x16x32_bf16 v[98:101], v[186:189], v[242:245], v[98:101]
	s_setprio 0
	s_setprio 1
	v_mfma_f32_16x16x32_bf16 v[68:71], v[190:193], v[206:209], v[68:71]
	v_mfma_f32_16x16x32_bf16 v[64:67], v[198:201], v[206:209], v[64:67]
	v_mfma_f32_16x16x32_bf16 v[52:55], v[190:193], v[214:217], v[52:55]
	v_mfma_f32_16x16x32_bf16 v[48:51], v[198:201], v[214:217], v[48:51]
	v_mfma_f32_16x16x32_bf16 v[44:47], v[190:193], v[222:225], v[44:47]
	v_mfma_f32_16x16x32_bf16 v[40:43], v[198:201], v[222:225], v[40:43]
	v_mfma_f32_16x16x32_bf16 v[36:39], v[190:193], v[230:233], v[36:39]
	v_mfma_f32_16x16x32_bf16 v[32:35], v[198:201], v[230:233], v[32:35]
	v_mfma_f32_16x16x32_bf16 v[68:71], v[194:197], v[210:213], v[68:71]
	v_mfma_f32_16x16x32_bf16 v[64:67], v[202:205], v[210:213], v[64:67]
	v_mfma_f32_16x16x32_bf16 v[52:55], v[194:197], v[218:221], v[52:55]
	v_mfma_f32_16x16x32_bf16 v[48:51], v[202:205], v[218:221], v[48:51]
	v_mfma_f32_16x16x32_bf16 v[44:47], v[194:197], v[226:229], v[44:47]
	v_mfma_f32_16x16x32_bf16 v[40:43], v[202:205], v[226:229], v[40:43]
	v_mfma_f32_16x16x32_bf16 v[36:39], v[194:197], v[242:245], v[36:39]
	v_mfma_f32_16x16x32_bf16 v[32:35], v[202:205], v[242:245], v[32:35]
	s_setprio 0
	s_barrier
	s_setprio 2
	s_add_i32 s28, s57, s36
	v_lshl_add_u64 v[152:153], v[152:153], 0, s[16:17]
	s_mov_b32 m0, s28
	ds_read_b128 v[206:209], v150 offset:49152
	ds_read_b128 v[210:213], v150 offset:50176
	ds_read_b128 v[214:217], v150 offset:51200
	ds_read_b128 v[218:221], v150 offset:52224
	ds_read_b128 v[222:225], v150 offset:53248
	ds_read_b128 v[226:229], v150 offset:54272
	ds_read_b128 v[230:233], v150 offset:55296
	ds_read_b128 v[242:245], v150 offset:56320
	global_load_lds_dwordx4 v[152:153], off
	s_add_i32 m0, s28, 0x2000
	s_add_u32 s26, s26, 0x40080
	v_lshl_add_u64 v[152:153], v[154:155], 0, s[16:17]
	s_addc_u32 s27, s27, 0
	s_add_i32 s28, s58, s36
	global_load_lds_dwordx4 v[152:153], off
	v_lshl_add_u64 v[152:153], s[26:27], 0, v[96:97]
	s_mov_b32 m0, s28
	s_nop 0
	global_load_lds_dwordx4 v[152:153], off
	v_lshl_add_u64 v[152:153], s[26:27], 0, v[130:131]
	s_add_i32 m0, s28, 0x2000
	s_nop 0
	global_load_lds_dwordx4 v[152:153], off
	v_lshl_add_u64 v[152:153], v[156:157], 0, s[16:17]
	s_mov_b32 m0, s45
	s_nop 0
	global_load_lds_dwordx4 v[152:153], off
	v_lshl_add_u64 v[152:153], v[158:159], 0, s[16:17]
	s_mov_b32 m0, s46
	s_nop 0
	global_load_lds_dwordx4 v[152:153], off
	s_waitcnt vmcnt(8) lgkmcnt(0)
	s_barrier
	s_setprio 1
	v_mfma_f32_16x16x32_bf16 v[92:95], v[162:165], v[206:209], v[92:95]
	v_mfma_f32_16x16x32_bf16 v[88:91], v[170:173], v[206:209], v[88:91]
	v_mfma_f32_16x16x32_bf16 v[84:87], v[162:165], v[214:217], v[84:87]
	v_mfma_f32_16x16x32_bf16 v[80:83], v[170:173], v[214:217], v[80:83]
	v_mfma_f32_16x16x32_bf16 v[76:79], v[162:165], v[222:225], v[76:79]
	v_mfma_f32_16x16x32_bf16 v[72:75], v[170:173], v[222:225], v[72:75]
	v_mfma_f32_16x16x32_bf16 v[60:63], v[162:165], v[230:233], v[60:63]
	v_mfma_f32_16x16x32_bf16 v[56:59], v[170:173], v[230:233], v[56:59]
	v_mfma_f32_16x16x32_bf16 v[92:95], v[166:169], v[210:213], v[92:95]
	v_mfma_f32_16x16x32_bf16 v[88:91], v[186:189], v[210:213], v[88:91]
	v_mfma_f32_16x16x32_bf16 v[84:87], v[166:169], v[218:221], v[84:87]
	v_mfma_f32_16x16x32_bf16 v[80:83], v[186:189], v[218:221], v[80:83]
	v_mfma_f32_16x16x32_bf16 v[76:79], v[166:169], v[226:229], v[76:79]
	v_mfma_f32_16x16x32_bf16 v[72:75], v[186:189], v[226:229], v[72:75]
	v_mfma_f32_16x16x32_bf16 v[60:63], v[166:169], v[242:245], v[60:63]
	v_mfma_f32_16x16x32_bf16 v[56:59], v[186:189], v[242:245], v[56:59]
	s_setprio 0
	s_setprio 1
	v_mfma_f32_16x16x32_bf16 v[28:31], v[190:193], v[206:209], v[28:31]
	v_mfma_f32_16x16x32_bf16 v[24:27], v[198:201], v[206:209], v[24:27]
	v_mfma_f32_16x16x32_bf16 v[20:23], v[190:193], v[214:217], v[20:23]
	v_mfma_f32_16x16x32_bf16 v[16:19], v[198:201], v[214:217], v[16:19]
	v_mfma_f32_16x16x32_bf16 v[12:15], v[190:193], v[222:225], v[12:15]
	v_mfma_f32_16x16x32_bf16 v[8:11], v[198:201], v[222:225], v[8:11]
	v_mfma_f32_16x16x32_bf16 v[4:7], v[190:193], v[230:233], v[4:7]
	v_mfma_f32_16x16x32_bf16 v[0:3], v[198:201], v[230:233], v[0:3]
	v_mfma_f32_16x16x32_bf16 v[28:31], v[194:197], v[210:213], v[28:31]
	v_mfma_f32_16x16x32_bf16 v[24:27], v[202:205], v[210:213], v[24:27]
	v_mfma_f32_16x16x32_bf16 v[20:23], v[194:197], v[218:221], v[20:23]
	v_mfma_f32_16x16x32_bf16 v[16:19], v[202:205], v[218:221], v[16:19]
	v_mfma_f32_16x16x32_bf16 v[12:15], v[194:197], v[226:229], v[12:15]
	v_mfma_f32_16x16x32_bf16 v[8:11], v[202:205], v[226:229], v[8:11]
	v_mfma_f32_16x16x32_bf16 v[4:7], v[194:197], v[242:245], v[4:7]
	v_mfma_f32_16x16x32_bf16 v[0:3], v[202:205], v[242:245], v[0:3]
	s_setprio 0
	s_barrier
	s_setprio 2
	s_add_i32 s56, s56, 2
	s_add_u32 s14, s14, 0x100
	s_addc_u32 s15, s15, 0
	s_add_u32 s54, s54, 0x100
	s_addc_u32 s55, s55, 0
	s_cmp_gt_u32 s56, 13
	s_cbranch_scc0 .LBB0_393
	s_and_b64 vcc, exec, s[12:13]
	s_cbranch_vccz .LBB0_396
	s_barrier

.LBB0_427:
	s_add_u32 s14, s4, 0xfffc0080
	s_addc_u32 s15, s5, -1
	s_add_i32 s62, 0, 0x10000
	s_cmp_eq_u32 s61, 12
	s_cselect_b32 s37, s29, s15
	s_cselect_b32 s36, s57, s14
	v_add_u32_e32 v154, s62, v169
	s_cselect_b32 s15, s27, s60
	s_cselect_b32 s14, s58, s59
	s_add_i32 s64, 0, 0x14000
	ds_read_b128 v[142:145], v154
	ds_read_b128 v[146:149], v154 offset:1024
	ds_read_b128 v[150:153], v154 offset:2048
	ds_read_b128 v[162:165], v154 offset:3072
	v_add_u32_e32 v154, s64, v169
	ds_read_b128 v[186:189], v154
	ds_read_b128 v[190:193], v154 offset:1024
	ds_read_b128 v[194:197], v154 offset:2048
	ds_read_b128 v[198:201], v154 offset:3072
	v_lshl_add_u64 v[154:155], s[4:5], 0, v[138:139]
	s_add_i32 m0, s43, 0xc000
	ds_read_b128 v[202:205], v173
	ds_read_b128 v[206:209], v173 offset:1024
	ds_read_b128 v[210:213], v173 offset:2048
	ds_read_b128 v[214:217], v173 offset:3072
	ds_read_b128 v[218:221], v173 offset:4096
	ds_read_b128 v[222:225], v173 offset:5120
	ds_read_b128 v[226:229], v173 offset:6144
	ds_read_b128 v[230:233], v173 offset:7168
	global_load_lds_dwordx4 v[154:155], off
	v_lshl_add_u64 v[154:155], s[4:5], 0, v[140:141]
	s_add_i32 m0, s43, 0xe000
	s_nop 0
	global_load_lds_dwordx4 v[154:155], off
	s_waitcnt vmcnt(8) lgkmcnt(0)
	s_barrier
	s_setprio 1
	v_mfma_f32_16x16x32_bf16 v[126:129], v[142:145], v[202:205], v[126:129]
	v_mfma_f32_16x16x32_bf16 v[122:125], v[150:153], v[202:205], v[122:125]
	v_mfma_f32_16x16x32_bf16 v[110:113], v[142:145], v[210:213], v[110:113]
	v_mfma_f32_16x16x32_bf16 v[106:109], v[150:153], v[210:213], v[106:109]
	v_mfma_f32_16x16x32_bf16 v[92:95], v[142:145], v[218:221], v[92:95]
	v_mfma_f32_16x16x32_bf16 v[88:91], v[150:153], v[218:221], v[88:91]
	v_mfma_f32_16x16x32_bf16 v[76:79], v[142:145], v[226:229], v[76:79]
	v_mfma_f32_16x16x32_bf16 v[72:75], v[150:153], v[226:229], v[72:75]
	v_mfma_f32_16x16x32_bf16 v[126:129], v[146:149], v[206:209], v[126:129]
	v_mfma_f32_16x16x32_bf16 v[122:125], v[162:165], v[206:209], v[122:125]
	v_mfma_f32_16x16x32_bf16 v[110:113], v[146:149], v[214:217], v[110:113]
	v_mfma_f32_16x16x32_bf16 v[106:109], v[162:165], v[214:217], v[106:109]
	v_mfma_f32_16x16x32_bf16 v[92:95], v[146:149], v[222:225], v[92:95]
	v_mfma_f32_16x16x32_bf16 v[88:91], v[162:165], v[222:225], v[88:91]
	v_mfma_f32_16x16x32_bf16 v[76:79], v[146:149], v[230:233], v[76:79]
	v_mfma_f32_16x16x32_bf16 v[72:75], v[162:165], v[230:233], v[72:75]
	s_setprio 0
	s_setprio 1
	v_mfma_f32_16x16x32_bf16 v[118:121], v[186:189], v[202:205], v[118:121]
	v_mfma_f32_16x16x32_bf16 v[114:117], v[194:197], v[202:205], v[114:117]
	v_mfma_f32_16x16x32_bf16 v[102:105], v[186:189], v[210:213], v[102:105]
	v_mfma_f32_16x16x32_bf16 v[98:101], v[194:197], v[210:213], v[98:101]
	v_mfma_f32_16x16x32_bf16 v[84:87], v[186:189], v[218:221], v[84:87]
	v_mfma_f32_16x16x32_bf16 v[80:83], v[194:197], v[218:221], v[80:83]
	v_mfma_f32_16x16x32_bf16 v[68:71], v[186:189], v[226:229], v[68:71]
	v_mfma_f32_16x16x32_bf16 v[64:67], v[194:197], v[226:229], v[64:67]
	v_mfma_f32_16x16x32_bf16 v[118:121], v[190:193], v[206:209], v[118:121]
	v_mfma_f32_16x16x32_bf16 v[114:117], v[198:201], v[206:209], v[114:117]
	v_mfma_f32_16x16x32_bf16 v[102:105], v[190:193], v[214:217], v[102:105]
	v_mfma_f32_16x16x32_bf16 v[98:101], v[198:201], v[214:217], v[98:101]
	v_mfma_f32_16x16x32_bf16 v[84:87], v[190:193], v[222:225], v[84:87]
	v_mfma_f32_16x16x32_bf16 v[80:83], v[198:201], v[222:225], v[80:83]
	v_mfma_f32_16x16x32_bf16 v[68:71], v[190:193], v[230:233], v[68:71]
	v_mfma_f32_16x16x32_bf16 v[64:67], v[198:201], v[230:233], v[64:67]
	s_setprio 0
	s_barrier
	s_setprio 2
	s_add_i32 s62, s62, s42
	v_lshl_add_u64 v[154:155], s[14:15], 0, v[96:97]
	s_mov_b32 m0, s62
	ds_read_b128 v[202:205], v173 offset:16384
	ds_read_b128 v[206:209], v173 offset:17408
	ds_read_b128 v[210:213], v173 offset:18432
	ds_read_b128 v[214:217], v173 offset:19456
	ds_read_b128 v[218:221], v173 offset:20480
	ds_read_b128 v[222:225], v173 offset:21504
	ds_read_b128 v[226:229], v173 offset:22528
	ds_read_b128 v[230:233], v173 offset:23552
	global_load_lds_dwordx4 v[154:155], off
	s_add_i32 m0, s62, 0x2000
	s_add_u32 s62, s14, 0x40000
	v_lshl_add_u64 v[156:157], s[14:15], 0, v[130:131]
	s_addc_u32 s63, s15, 0
	s_add_i32 s64, s64, s42
	global_load_lds_dwordx4 v[156:157], off
	v_lshl_add_u64 v[158:159], s[62:63], 0, v[96:97]
	s_mov_b32 m0, s64
	v_lshl_add_u64 v[166:167], s[36:37], 0, v[132:133]
	global_load_lds_dwordx4 v[158:159], off
	v_lshl_add_u64 v[158:159], s[62:63], 0, v[130:131]
	s_add_i32 m0, s64, 0x2000
	s_nop 0
	global_load_lds_dwordx4 v[158:159], off
	v_lshl_add_u64 v[158:159], s[36:37], 0, v[134:135]
	s_mov_b32 m0, s43
	s_nop 0
	global_load_lds_dwordx4 v[158:159], off
	s_mov_b32 m0, s44
	s_nop 0
	global_load_lds_dwordx4 v[166:167], off
	s_waitcnt vmcnt(8) lgkmcnt(0)
	s_barrier
	s_setprio 1
	v_mfma_f32_16x16x32_bf16 v[60:63], v[142:145], v[202:205], v[60:63]
	v_mfma_f32_16x16x32_bf16 v[56:59], v[150:153], v[202:205], v[56:59]
	v_mfma_f32_16x16x32_bf16 v[44:47], v[142:145], v[210:213], v[44:47]
	v_mfma_f32_16x16x32_bf16 v[40:43], v[150:153], v[210:213], v[40:43]
	v_mfma_f32_16x16x32_bf16 v[28:31], v[142:145], v[218:221], v[28:31]
	v_mfma_f32_16x16x32_bf16 v[24:27], v[150:153], v[218:221], v[24:27]
	v_mfma_f32_16x16x32_bf16 v[12:15], v[142:145], v[226:229], v[12:15]
	v_mfma_f32_16x16x32_bf16 v[8:11], v[150:153], v[226:229], v[8:11]
	v_mfma_f32_16x16x32_bf16 v[60:63], v[146:149], v[206:209], v[60:63]
	v_mfma_f32_16x16x32_bf16 v[56:59], v[162:165], v[206:209], v[56:59]
	v_mfma_f32_16x16x32_bf16 v[44:47], v[146:149], v[214:217], v[44:47]
	v_mfma_f32_16x16x32_bf16 v[40:43], v[162:165], v[214:217], v[40:43]
	v_mfma_f32_16x16x32_bf16 v[28:31], v[146:149], v[222:225], v[28:31]
	v_mfma_f32_16x16x32_bf16 v[24:27], v[162:165], v[222:225], v[24:27]
	v_mfma_f32_16x16x32_bf16 v[12:15], v[146:149], v[230:233], v[12:15]
	v_mfma_f32_16x16x32_bf16 v[8:11], v[162:165], v[230:233], v[8:11]
	s_setprio 0
	s_setprio 1
	v_mfma_f32_16x16x32_bf16 v[52:55], v[186:189], v[202:205], v[52:55]
	v_mfma_f32_16x16x32_bf16 v[48:51], v[194:197], v[202:205], v[48:51]
	v_mfma_f32_16x16x32_bf16 v[36:39], v[186:189], v[210:213], v[36:39]
	v_mfma_f32_16x16x32_bf16 v[32:35], v[194:197], v[210:213], v[32:35]
	v_mfma_f32_16x16x32_bf16 v[20:23], v[186:189], v[218:221], v[20:23]
	v_mfma_f32_16x16x32_bf16 v[16:19], v[194:197], v[218:221], v[16:19]
	v_mfma_f32_16x16x32_bf16 v[4:7], v[186:189], v[226:229], v[4:7]
	v_mfma_f32_16x16x32_bf16 v[0:3], v[194:197], v[226:229], v[0:3]
	v_mfma_f32_16x16x32_bf16 v[52:55], v[190:193], v[206:209], v[52:55]
	v_mfma_f32_16x16x32_bf16 v[48:51], v[198:201], v[206:209], v[48:51]
	v_mfma_f32_16x16x32_bf16 v[36:39], v[190:193], v[214:217], v[36:39]
	v_mfma_f32_16x16x32_bf16 v[32:35], v[198:201], v[214:217], v[32:35]
	v_mfma_f32_16x16x32_bf16 v[20:23], v[190:193], v[222:225], v[20:23]
	v_mfma_f32_16x16x32_bf16 v[16:19], v[198:201], v[222:225], v[16:19]
	v_mfma_f32_16x16x32_bf16 v[4:7], v[190:193], v[230:233], v[4:7]
	v_mfma_f32_16x16x32_bf16 v[0:3], v[198:201], v[230:233], v[0:3]
	s_setprio 0
	s_barrier
	s_setprio 2
	s_add_i32 s62, 0, 0x18000
	s_add_i32 s63, 0, 0x1c000
	v_add_u32_e32 v162, s62, v169
	v_add_u32_e32 v182, s63, v169
	ds_read_b128 v[142:145], v162
	ds_read_b128 v[146:149], v162 offset:1024
	ds_read_b128 v[150:153], v162 offset:2048
	ds_read_b128 v[162:165], v162 offset:3072
	ds_read_b128 v[186:189], v182
	ds_read_b128 v[190:193], v182 offset:1024
	ds_read_b128 v[194:197], v182 offset:2048
	ds_read_b128 v[198:201], v182 offset:3072
	s_add_u32 s36, s36, 0x40000
	s_addc_u32 s37, s37, 0
	s_mov_b32 m0, s45
	v_lshl_add_u64 v[182:183], s[36:37], 0, v[134:135]
	ds_read_b128 v[202:205], v173 offset:32768
	ds_read_b128 v[206:209], v173 offset:33792
	ds_read_b128 v[210:213], v173 offset:34816
	ds_read_b128 v[214:217], v173 offset:35840
	ds_read_b128 v[218:221], v173 offset:36864
	ds_read_b128 v[222:225], v173 offset:37888
	ds_read_b128 v[226:229], v173 offset:38912
	ds_read_b128 v[230:233], v173 offset:39936
	global_load_lds_dwordx4 v[182:183], off
	v_lshl_add_u64 v[182:183], s[36:37], 0, v[132:133]
	s_mov_b32 m0, s46
	s_nop 0
	global_load_lds_dwordx4 v[182:183], off
	s_waitcnt vmcnt(8) lgkmcnt(0)
	s_barrier
	s_setprio 1
	v_mfma_f32_16x16x32_bf16 v[126:129], v[142:145], v[202:205], v[126:129]
	v_mfma_f32_16x16x32_bf16 v[122:125], v[150:153], v[202:205], v[122:125]
	v_mfma_f32_16x16x32_bf16 v[110:113], v[142:145], v[210:213], v[110:113]
	v_mfma_f32_16x16x32_bf16 v[106:109], v[150:153], v[210:213], v[106:109]
	v_mfma_f32_16x16x32_bf16 v[92:95], v[142:145], v[218:221], v[92:95]
	v_mfma_f32_16x16x32_bf16 v[88:91], v[150:153], v[218:221], v[88:91]
	v_mfma_f32_16x16x32_bf16 v[76:79], v[142:145], v[226:229], v[76:79]
	v_mfma_f32_16x16x32_bf16 v[72:75], v[150:153], v[226:229], v[72:75]
	v_mfma_f32_16x16x32_bf16 v[126:129], v[146:149], v[206:209], v[126:129]
	v_mfma_f32_16x16x32_bf16 v[122:125], v[162:165], v[206:209], v[122:125]
	v_mfma_f32_16x16x32_bf16 v[110:113], v[146:149], v[214:217], v[110:113]
	v_mfma_f32_16x16x32_bf16 v[106:109], v[162:165], v[214:217], v[106:109]
	v_mfma_f32_16x16x32_bf16 v[92:95], v[146:149], v[222:225], v[92:95]
	v_mfma_f32_16x16x32_bf16 v[88:91], v[162:165], v[222:225], v[88:91]
	v_mfma_f32_16x16x32_bf16 v[76:79], v[146:149], v[230:233], v[76:79]
	v_mfma_f32_16x16x32_bf16 v[72:75], v[162:165], v[230:233], v[72:75]
	s_setprio 0
	s_setprio 1
	v_mfma_f32_16x16x32_bf16 v[118:121], v[186:189], v[202:205], v[118:121]
	v_mfma_f32_16x16x32_bf16 v[114:117], v[194:197], v[202:205], v[114:117]
	v_mfma_f32_16x16x32_bf16 v[102:105], v[186:189], v[210:213], v[102:105]
	v_mfma_f32_16x16x32_bf16 v[98:101], v[194:197], v[210:213], v[98:101]
	v_mfma_f32_16x16x32_bf16 v[84:87], v[186:189], v[218:221], v[84:87]
	v_mfma_f32_16x16x32_bf16 v[80:83], v[194:197], v[218:221], v[80:83]
	v_mfma_f32_16x16x32_bf16 v[68:71], v[186:189], v[226:229], v[68:71]
	v_mfma_f32_16x16x32_bf16 v[64:67], v[194:197], v[226:229], v[64:67]
	v_mfma_f32_16x16x32_bf16 v[118:121], v[190:193], v[206:209], v[118:121]
	v_mfma_f32_16x16x32_bf16 v[114:117], v[198:201], v[206:209], v[114:117]
	v_mfma_f32_16x16x32_bf16 v[102:105], v[190:193], v[214:217], v[102:105]
	v_mfma_f32_16x16x32_bf16 v[98:101], v[198:201], v[214:217], v[98:101]
	v_mfma_f32_16x16x32_bf16 v[84:87], v[190:193], v[222:225], v[84:87]
	v_mfma_f32_16x16x32_bf16 v[80:83], v[198:201], v[222:225], v[80:83]
	v_mfma_f32_16x16x32_bf16 v[68:71], v[190:193], v[230:233], v[68:71]
	v_mfma_f32_16x16x32_bf16 v[64:67], v[198:201], v[230:233], v[64:67]
	s_setprio 0
	s_barrier
	s_setprio 2
	s_add_i32 s36, s62, s42
	v_lshl_add_u64 v[154:155], v[154:155], 0, s[16:17]
	s_mov_b32 m0, s36
	ds_read_b128 v[202:205], v173 offset:49152
	ds_read_b128 v[206:209], v173 offset:50176
	ds_read_b128 v[210:213], v173 offset:51200
	ds_read_b128 v[214:217], v173 offset:52224
	ds_read_b128 v[218:221], v173 offset:53248
	ds_read_b128 v[222:225], v173 offset:54272
	ds_read_b128 v[226:229], v173 offset:55296
	ds_read_b128 v[230:233], v173 offset:56320
	global_load_lds_dwordx4 v[154:155], off
	s_add_i32 m0, s36, 0x2000
	s_add_u32 s14, s14, 0x40080
	v_lshl_add_u64 v[154:155], v[156:157], 0, s[16:17]
	s_addc_u32 s15, s15, 0
	s_add_i32 s36, s63, s42
	global_load_lds_dwordx4 v[154:155], off
	v_lshl_add_u64 v[154:155], s[14:15], 0, v[96:97]
	s_mov_b32 m0, s36
	s_nop 0
	global_load_lds_dwordx4 v[154:155], off
	v_lshl_add_u64 v[154:155], s[14:15], 0, v[130:131]
	s_add_i32 m0, s36, 0x2000
	s_nop 0
	global_load_lds_dwordx4 v[154:155], off
	v_lshl_add_u64 v[154:155], v[158:159], 0, s[16:17]
	s_mov_b32 m0, s52
	s_nop 0
	global_load_lds_dwordx4 v[154:155], off
	v_lshl_add_u64 v[154:155], v[166:167], 0, s[16:17]
	s_mov_b32 m0, s53
	s_nop 0
	global_load_lds_dwordx4 v[154:155], off
	s_waitcnt vmcnt(8) lgkmcnt(0)
	s_barrier
	s_setprio 1
	v_mfma_f32_16x16x32_bf16 v[60:63], v[142:145], v[202:205], v[60:63]
	v_mfma_f32_16x16x32_bf16 v[56:59], v[150:153], v[202:205], v[56:59]
	v_mfma_f32_16x16x32_bf16 v[44:47], v[142:145], v[210:213], v[44:47]
	v_mfma_f32_16x16x32_bf16 v[40:43], v[150:153], v[210:213], v[40:43]
	v_mfma_f32_16x16x32_bf16 v[28:31], v[142:145], v[218:221], v[28:31]
	v_mfma_f32_16x16x32_bf16 v[24:27], v[150:153], v[218:221], v[24:27]
	v_mfma_f32_16x16x32_bf16 v[12:15], v[142:145], v[226:229], v[12:15]
	v_mfma_f32_16x16x32_bf16 v[8:11], v[150:153], v[226:229], v[8:11]
	v_mfma_f32_16x16x32_bf16 v[60:63], v[146:149], v[206:209], v[60:63]
	v_mfma_f32_16x16x32_bf16 v[56:59], v[162:165], v[206:209], v[56:59]
	v_mfma_f32_16x16x32_bf16 v[44:47], v[146:149], v[214:217], v[44:47]
	v_mfma_f32_16x16x32_bf16 v[40:43], v[162:165], v[214:217], v[40:43]
	v_mfma_f32_16x16x32_bf16 v[28:31], v[146:149], v[222:225], v[28:31]
	v_mfma_f32_16x16x32_bf16 v[24:27], v[162:165], v[222:225], v[24:27]
	v_mfma_f32_16x16x32_bf16 v[12:15], v[146:149], v[230:233], v[12:15]
	v_mfma_f32_16x16x32_bf16 v[8:11], v[162:165], v[230:233], v[8:11]
	s_setprio 0
	s_setprio 1
	v_mfma_f32_16x16x32_bf16 v[52:55], v[186:189], v[202:205], v[52:55]
	v_mfma_f32_16x16x32_bf16 v[48:51], v[194:197], v[202:205], v[48:51]
	v_mfma_f32_16x16x32_bf16 v[36:39], v[186:189], v[210:213], v[36:39]
	v_mfma_f32_16x16x32_bf16 v[32:35], v[194:197], v[210:213], v[32:35]
	v_mfma_f32_16x16x32_bf16 v[20:23], v[186:189], v[218:221], v[20:23]
	v_mfma_f32_16x16x32_bf16 v[16:19], v[194:197], v[218:221], v[16:19]
	v_mfma_f32_16x16x32_bf16 v[4:7], v[186:189], v[226:229], v[4:7]
	v_mfma_f32_16x16x32_bf16 v[0:3], v[194:197], v[226:229], v[0:3]
	v_mfma_f32_16x16x32_bf16 v[52:55], v[190:193], v[206:209], v[52:55]
	v_mfma_f32_16x16x32_bf16 v[48:51], v[198:201], v[206:209], v[48:51]
	v_mfma_f32_16x16x32_bf16 v[36:39], v[190:193], v[214:217], v[36:39]
	v_mfma_f32_16x16x32_bf16 v[32:35], v[198:201], v[214:217], v[32:35]
	v_mfma_f32_16x16x32_bf16 v[20:23], v[190:193], v[222:225], v[20:23]
	v_mfma_f32_16x16x32_bf16 v[16:19], v[198:201], v[222:225], v[16:19]
	v_mfma_f32_16x16x32_bf16 v[4:7], v[190:193], v[230:233], v[4:7]
	v_mfma_f32_16x16x32_bf16 v[0:3], v[198:201], v[230:233], v[0:3]
	s_setprio 0
	s_barrier
	s_setprio 2
	s_add_i32 s61, s61, 2
	s_add_u32 s4, s4, 0x100
	s_addc_u32 s5, s5, 0
	s_add_u32 s59, s59, 0x100
	s_addc_u32 s60, s60, 0
	s_cmp_gt_u32 s61, 13
	s_cbranch_scc0 .LBB0_427
	s_and_b64 vcc, exec, s[24:25]
	s_cbranch_vccz .LBB0_430
	s_barrier

.LBB0_449:
	s_add_u32 s30, s14, 0xfffc0080
	s_addc_u32 s31, s15, -1
	s_add_i32 s60, 0, 0x10000
	s_cmp_eq_u32 s59, 12
	s_cselect_b32 s35, s25, s31
	s_cselect_b32 s34, s55, s30
	v_add_u32_e32 v96, s60, v151
	s_cselect_b32 s31, s13, s58
	s_cselect_b32 s30, s56, s57
	s_add_i32 s62, 0, 0x14000
	ds_read_b128 v[144:147], v96
	ds_read_b128 v[164:167], v96 offset:1024
	ds_read_b128 v[168:171], v96 offset:2048
	ds_read_b128 v[186:189], v96 offset:3072
	v_add_u32_e32 v96, s62, v151
	ds_read_b128 v[190:193], v96
	ds_read_b128 v[194:197], v96 offset:1024
	ds_read_b128 v[198:201], v96 offset:2048
	ds_read_b128 v[202:205], v96 offset:3072
	v_lshl_add_u64 v[148:149], s[14:15], 0, v[140:141]
	s_add_i32 m0, s41, 0xc000
	ds_read_b128 v[206:209], v163
	ds_read_b128 v[210:213], v163 offset:1024
	ds_read_b128 v[214:217], v163 offset:2048
	ds_read_b128 v[218:221], v163 offset:3072
	ds_read_b128 v[222:225], v163 offset:4096
	ds_read_b128 v[226:229], v163 offset:5120
	ds_read_b128 v[230:233], v163 offset:6144
	ds_read_b128 v[242:245], v163 offset:7168
	global_load_lds_dwordx4 v[148:149], off
	v_lshl_add_u64 v[148:149], s[14:15], 0, v[142:143]
	s_add_i32 m0, s41, 0xe000
	s_nop 0
	global_load_lds_dwordx4 v[148:149], off
	s_waitcnt vmcnt(8) lgkmcnt(0)
	s_barrier
	s_setprio 1
	v_mfma_f32_16x16x32_bf16 v[126:129], v[144:147], v[206:209], v[126:129]
	v_mfma_f32_16x16x32_bf16 v[122:125], v[168:171], v[206:209], v[122:125]
	v_mfma_f32_16x16x32_bf16 v[110:113], v[144:147], v[214:217], v[110:113]
	v_mfma_f32_16x16x32_bf16 v[106:109], v[168:171], v[214:217], v[106:109]
	v_mfma_f32_16x16x32_bf16 v[92:95], v[144:147], v[222:225], v[92:95]
	v_mfma_f32_16x16x32_bf16 v[88:91], v[168:171], v[222:225], v[88:91]
	v_mfma_f32_16x16x32_bf16 v[76:79], v[144:147], v[230:233], v[76:79]
	v_mfma_f32_16x16x32_bf16 v[72:75], v[168:171], v[230:233], v[72:75]
	v_mfma_f32_16x16x32_bf16 v[126:129], v[164:167], v[210:213], v[126:129]
	v_mfma_f32_16x16x32_bf16 v[122:125], v[186:189], v[210:213], v[122:125]
	v_mfma_f32_16x16x32_bf16 v[110:113], v[164:167], v[218:221], v[110:113]
	v_mfma_f32_16x16x32_bf16 v[106:109], v[186:189], v[218:221], v[106:109]
	v_mfma_f32_16x16x32_bf16 v[92:95], v[164:167], v[226:229], v[92:95]
	v_mfma_f32_16x16x32_bf16 v[88:91], v[186:189], v[226:229], v[88:91]
	v_mfma_f32_16x16x32_bf16 v[76:79], v[164:167], v[242:245], v[76:79]
	v_mfma_f32_16x16x32_bf16 v[72:75], v[186:189], v[242:245], v[72:75]
	s_setprio 0
	s_setprio 1
	v_mfma_f32_16x16x32_bf16 v[118:121], v[190:193], v[206:209], v[118:121]
	v_mfma_f32_16x16x32_bf16 v[114:117], v[198:201], v[206:209], v[114:117]
	v_mfma_f32_16x16x32_bf16 v[102:105], v[190:193], v[214:217], v[102:105]
	v_mfma_f32_16x16x32_bf16 v[98:101], v[198:201], v[214:217], v[98:101]
	v_mfma_f32_16x16x32_bf16 v[84:87], v[190:193], v[222:225], v[84:87]
	v_mfma_f32_16x16x32_bf16 v[80:83], v[198:201], v[222:225], v[80:83]
	v_mfma_f32_16x16x32_bf16 v[68:71], v[190:193], v[230:233], v[68:71]
	v_mfma_f32_16x16x32_bf16 v[64:67], v[198:201], v[230:233], v[64:67]
	v_mfma_f32_16x16x32_bf16 v[118:121], v[194:197], v[210:213], v[118:121]
	v_mfma_f32_16x16x32_bf16 v[114:117], v[202:205], v[210:213], v[114:117]
	v_mfma_f32_16x16x32_bf16 v[102:105], v[194:197], v[218:221], v[102:105]
	v_mfma_f32_16x16x32_bf16 v[98:101], v[202:205], v[218:221], v[98:101]
	v_mfma_f32_16x16x32_bf16 v[84:87], v[194:197], v[226:229], v[84:87]
	v_mfma_f32_16x16x32_bf16 v[80:83], v[202:205], v[226:229], v[80:83]
	v_mfma_f32_16x16x32_bf16 v[68:71], v[194:197], v[242:245], v[68:71]
	v_mfma_f32_16x16x32_bf16 v[64:67], v[202:205], v[242:245], v[64:67]
	s_setprio 0
	s_barrier
	s_setprio 2
	s_add_i32 s60, s60, s40
	v_lshl_add_u64 v[148:149], s[30:31], 0, v[134:135]
	s_mov_b32 m0, s60
	ds_read_b128 v[206:209], v163 offset:16384
	ds_read_b128 v[210:213], v163 offset:17408
	ds_read_b128 v[214:217], v163 offset:18432
	ds_read_b128 v[218:221], v163 offset:19456
	ds_read_b128 v[222:225], v163 offset:20480
	ds_read_b128 v[226:229], v163 offset:21504
	ds_read_b128 v[230:233], v163 offset:22528
	ds_read_b128 v[242:245], v163 offset:23552
	global_load_lds_dwordx4 v[148:149], off
	s_add_i32 m0, s60, 0x2000
	s_add_u32 s60, s30, 0x40000
	v_lshl_add_u64 v[154:155], s[30:31], 0, v[130:131]
	s_addc_u32 s61, s31, 0
	s_add_i32 s62, s62, s40
	global_load_lds_dwordx4 v[154:155], off
	v_lshl_add_u64 v[156:157], s[60:61], 0, v[134:135]
	s_mov_b32 m0, s62
	v_lshl_add_u64 v[158:159], s[34:35], 0, v[132:133]
	global_load_lds_dwordx4 v[156:157], off
	v_lshl_add_u64 v[156:157], s[60:61], 0, v[130:131]
	s_add_i32 m0, s62, 0x2000
	s_nop 0
	global_load_lds_dwordx4 v[156:157], off
	v_lshl_add_u64 v[156:157], s[34:35], 0, v[136:137]
	s_mov_b32 m0, s41
	s_nop 0
	global_load_lds_dwordx4 v[156:157], off
	s_mov_b32 m0, s42
	s_nop 0
	global_load_lds_dwordx4 v[158:159], off
	s_waitcnt vmcnt(8) lgkmcnt(0)
	s_barrier
	s_setprio 1
	v_mfma_f32_16x16x32_bf16 v[60:63], v[144:147], v[206:209], v[60:63]
	v_mfma_f32_16x16x32_bf16 v[56:59], v[168:171], v[206:209], v[56:59]
	v_mfma_f32_16x16x32_bf16 v[44:47], v[144:147], v[214:217], v[44:47]
	v_mfma_f32_16x16x32_bf16 v[40:43], v[168:171], v[214:217], v[40:43]
	v_mfma_f32_16x16x32_bf16 v[28:31], v[144:147], v[222:225], v[28:31]
	v_mfma_f32_16x16x32_bf16 v[24:27], v[168:171], v[222:225], v[24:27]
	v_mfma_f32_16x16x32_bf16 v[12:15], v[144:147], v[230:233], v[12:15]
	v_mfma_f32_16x16x32_bf16 v[8:11], v[168:171], v[230:233], v[8:11]
	v_mfma_f32_16x16x32_bf16 v[60:63], v[164:167], v[210:213], v[60:63]
	v_mfma_f32_16x16x32_bf16 v[56:59], v[186:189], v[210:213], v[56:59]
	v_mfma_f32_16x16x32_bf16 v[44:47], v[164:167], v[218:221], v[44:47]
	v_mfma_f32_16x16x32_bf16 v[40:43], v[186:189], v[218:221], v[40:43]
	v_mfma_f32_16x16x32_bf16 v[28:31], v[164:167], v[226:229], v[28:31]
	v_mfma_f32_16x16x32_bf16 v[24:27], v[186:189], v[226:229], v[24:27]
	v_mfma_f32_16x16x32_bf16 v[12:15], v[164:167], v[242:245], v[12:15]
	v_mfma_f32_16x16x32_bf16 v[8:11], v[186:189], v[242:245], v[8:11]
	s_setprio 0
	s_setprio 1
	v_mfma_f32_16x16x32_bf16 v[52:55], v[190:193], v[206:209], v[52:55]
	v_mfma_f32_16x16x32_bf16 v[48:51], v[198:201], v[206:209], v[48:51]
	v_mfma_f32_16x16x32_bf16 v[36:39], v[190:193], v[214:217], v[36:39]
	v_mfma_f32_16x16x32_bf16 v[32:35], v[198:201], v[214:217], v[32:35]
	v_mfma_f32_16x16x32_bf16 v[20:23], v[190:193], v[222:225], v[20:23]
	v_mfma_f32_16x16x32_bf16 v[16:19], v[198:201], v[222:225], v[16:19]
	v_mfma_f32_16x16x32_bf16 v[4:7], v[190:193], v[230:233], v[4:7]
	v_mfma_f32_16x16x32_bf16 v[0:3], v[198:201], v[230:233], v[0:3]
	v_mfma_f32_16x16x32_bf16 v[52:55], v[194:197], v[210:213], v[52:55]
	v_mfma_f32_16x16x32_bf16 v[48:51], v[202:205], v[210:213], v[48:51]
	v_mfma_f32_16x16x32_bf16 v[36:39], v[194:197], v[218:221], v[36:39]
	v_mfma_f32_16x16x32_bf16 v[32:35], v[202:205], v[218:221], v[32:35]
	v_mfma_f32_16x16x32_bf16 v[20:23], v[194:197], v[226:229], v[20:23]
	v_mfma_f32_16x16x32_bf16 v[16:19], v[202:205], v[226:229], v[16:19]
	v_mfma_f32_16x16x32_bf16 v[4:7], v[194:197], v[242:245], v[4:7]
	v_mfma_f32_16x16x32_bf16 v[0:3], v[202:205], v[242:245], v[0:3]
	s_setprio 0
	s_barrier
	s_setprio 2
	s_add_i32 s60, 0, 0x18000
	v_add_u32_e32 v96, s60, v151
	s_add_i32 s61, 0, 0x1c000
	ds_read_b128 v[144:147], v96
	ds_read_b128 v[164:167], v96 offset:1024
	ds_read_b128 v[168:171], v96 offset:2048
	ds_read_b128 v[186:189], v96 offset:3072
	v_add_u32_e32 v96, s61, v151
	ds_read_b128 v[190:193], v96
	ds_read_b128 v[194:197], v96 offset:1024
	ds_read_b128 v[198:201], v96 offset:2048
	ds_read_b128 v[202:205], v96 offset:3072
	s_add_u32 s34, s34, 0x40000
	s_addc_u32 s35, s35, 0
	s_mov_b32 m0, s43
	v_lshl_add_u64 v[172:173], s[34:35], 0, v[136:137]
	ds_read_b128 v[206:209], v163 offset:32768
	ds_read_b128 v[210:213], v163 offset:33792
	ds_read_b128 v[214:217], v163 offset:34816
	ds_read_b128 v[218:221], v163 offset:35840
	ds_read_b128 v[222:225], v163 offset:36864
	ds_read_b128 v[226:229], v163 offset:37888
	ds_read_b128 v[230:233], v163 offset:38912
	ds_read_b128 v[242:245], v163 offset:39936
	global_load_lds_dwordx4 v[172:173], off
	v_lshl_add_u64 v[172:173], s[34:35], 0, v[132:133]
	s_mov_b32 m0, s44
	s_nop 0
	global_load_lds_dwordx4 v[172:173], off
	s_waitcnt vmcnt(8) lgkmcnt(0)
	s_barrier
	s_setprio 1
	v_mfma_f32_16x16x32_bf16 v[126:129], v[144:147], v[206:209], v[126:129]
	v_mfma_f32_16x16x32_bf16 v[122:125], v[168:171], v[206:209], v[122:125]
	v_mfma_f32_16x16x32_bf16 v[110:113], v[144:147], v[214:217], v[110:113]
	v_mfma_f32_16x16x32_bf16 v[106:109], v[168:171], v[214:217], v[106:109]
	v_mfma_f32_16x16x32_bf16 v[92:95], v[144:147], v[222:225], v[92:95]
	v_mfma_f32_16x16x32_bf16 v[88:91], v[168:171], v[222:225], v[88:91]
	v_mfma_f32_16x16x32_bf16 v[76:79], v[144:147], v[230:233], v[76:79]
	v_mfma_f32_16x16x32_bf16 v[72:75], v[168:171], v[230:233], v[72:75]
	v_mfma_f32_16x16x32_bf16 v[126:129], v[164:167], v[210:213], v[126:129]
	v_mfma_f32_16x16x32_bf16 v[122:125], v[186:189], v[210:213], v[122:125]
	v_mfma_f32_16x16x32_bf16 v[110:113], v[164:167], v[218:221], v[110:113]
	v_mfma_f32_16x16x32_bf16 v[106:109], v[186:189], v[218:221], v[106:109]
	v_mfma_f32_16x16x32_bf16 v[92:95], v[164:167], v[226:229], v[92:95]
	v_mfma_f32_16x16x32_bf16 v[88:91], v[186:189], v[226:229], v[88:91]
	v_mfma_f32_16x16x32_bf16 v[76:79], v[164:167], v[242:245], v[76:79]
	v_mfma_f32_16x16x32_bf16 v[72:75], v[186:189], v[242:245], v[72:75]
	s_setprio 0
	s_setprio 1
	v_mfma_f32_16x16x32_bf16 v[118:121], v[190:193], v[206:209], v[118:121]
	v_mfma_f32_16x16x32_bf16 v[114:117], v[198:201], v[206:209], v[114:117]
	v_mfma_f32_16x16x32_bf16 v[102:105], v[190:193], v[214:217], v[102:105]
	v_mfma_f32_16x16x32_bf16 v[98:101], v[198:201], v[214:217], v[98:101]
	v_mfma_f32_16x16x32_bf16 v[84:87], v[190:193], v[222:225], v[84:87]
	v_mfma_f32_16x16x32_bf16 v[80:83], v[198:201], v[222:225], v[80:83]
	v_mfma_f32_16x16x32_bf16 v[68:71], v[190:193], v[230:233], v[68:71]
	v_mfma_f32_16x16x32_bf16 v[64:67], v[198:201], v[230:233], v[64:67]
	v_mfma_f32_16x16x32_bf16 v[118:121], v[194:197], v[210:213], v[118:121]
	v_mfma_f32_16x16x32_bf16 v[114:117], v[202:205], v[210:213], v[114:117]
	v_mfma_f32_16x16x32_bf16 v[102:105], v[194:197], v[218:221], v[102:105]
	v_mfma_f32_16x16x32_bf16 v[98:101], v[202:205], v[218:221], v[98:101]
	v_mfma_f32_16x16x32_bf16 v[84:87], v[194:197], v[226:229], v[84:87]
	v_mfma_f32_16x16x32_bf16 v[80:83], v[202:205], v[226:229], v[80:83]
	v_mfma_f32_16x16x32_bf16 v[68:71], v[194:197], v[242:245], v[68:71]
	v_mfma_f32_16x16x32_bf16 v[64:67], v[202:205], v[242:245], v[64:67]
	s_setprio 0
	s_barrier
	s_setprio 2
	s_add_i32 s34, s60, s40
	v_lshl_add_u64 v[148:149], v[148:149], 0, s[16:17]
	s_mov_b32 m0, s34
	ds_read_b128 v[206:209], v163 offset:49152
	ds_read_b128 v[210:213], v163 offset:50176
	ds_read_b128 v[214:217], v163 offset:51200
	ds_read_b128 v[218:221], v163 offset:52224
	ds_read_b128 v[222:225], v163 offset:53248
	ds_read_b128 v[226:229], v163 offset:54272
	ds_read_b128 v[230:233], v163 offset:55296
	ds_read_b128 v[242:245], v163 offset:56320
	global_load_lds_dwordx4 v[148:149], off
	s_add_i32 m0, s34, 0x2000
	s_add_u32 s30, s30, 0x40080
	v_lshl_add_u64 v[148:149], v[154:155], 0, s[16:17]
	s_addc_u32 s31, s31, 0
	s_add_i32 s34, s61, s40
	global_load_lds_dwordx4 v[148:149], off
	v_lshl_add_u64 v[148:149], s[30:31], 0, v[134:135]
	s_mov_b32 m0, s34
	s_nop 0
	global_load_lds_dwordx4 v[148:149], off
	v_lshl_add_u64 v[148:149], s[30:31], 0, v[130:131]
	s_add_i32 m0, s34, 0x2000
	s_nop 0
	global_load_lds_dwordx4 v[148:149], off
	v_lshl_add_u64 v[148:149], v[156:157], 0, s[16:17]
	s_mov_b32 m0, s49
	s_nop 0
	global_load_lds_dwordx4 v[148:149], off
	v_lshl_add_u64 v[148:149], v[158:159], 0, s[16:17]
	s_mov_b32 m0, s50
	s_nop 0
	global_load_lds_dwordx4 v[148:149], off
	s_waitcnt vmcnt(8) lgkmcnt(0)
	s_barrier
	s_setprio 1
	v_mfma_f32_16x16x32_bf16 v[60:63], v[144:147], v[206:209], v[60:63]
	v_mfma_f32_16x16x32_bf16 v[56:59], v[168:171], v[206:209], v[56:59]
	v_mfma_f32_16x16x32_bf16 v[44:47], v[144:147], v[214:217], v[44:47]
	v_mfma_f32_16x16x32_bf16 v[40:43], v[168:171], v[214:217], v[40:43]
	v_mfma_f32_16x16x32_bf16 v[28:31], v[144:147], v[222:225], v[28:31]
	v_mfma_f32_16x16x32_bf16 v[24:27], v[168:171], v[222:225], v[24:27]
	v_mfma_f32_16x16x32_bf16 v[12:15], v[144:147], v[230:233], v[12:15]
	v_mfma_f32_16x16x32_bf16 v[8:11], v[168:171], v[230:233], v[8:11]
	v_mfma_f32_16x16x32_bf16 v[60:63], v[164:167], v[210:213], v[60:63]
	v_mfma_f32_16x16x32_bf16 v[56:59], v[186:189], v[210:213], v[56:59]
	v_mfma_f32_16x16x32_bf16 v[44:47], v[164:167], v[218:221], v[44:47]
	v_mfma_f32_16x16x32_bf16 v[40:43], v[186:189], v[218:221], v[40:43]
	v_mfma_f32_16x16x32_bf16 v[28:31], v[164:167], v[226:229], v[28:31]
	v_mfma_f32_16x16x32_bf16 v[24:27], v[186:189], v[226:229], v[24:27]
	v_mfma_f32_16x16x32_bf16 v[12:15], v[164:167], v[242:245], v[12:15]
	v_mfma_f32_16x16x32_bf16 v[8:11], v[186:189], v[242:245], v[8:11]
	s_setprio 0
	s_setprio 1
	v_mfma_f32_16x16x32_bf16 v[52:55], v[190:193], v[206:209], v[52:55]
	v_mfma_f32_16x16x32_bf16 v[48:51], v[198:201], v[206:209], v[48:51]
	v_mfma_f32_16x16x32_bf16 v[36:39], v[190:193], v[214:217], v[36:39]
	v_mfma_f32_16x16x32_bf16 v[32:35], v[198:201], v[214:217], v[32:35]
	v_mfma_f32_16x16x32_bf16 v[20:23], v[190:193], v[222:225], v[20:23]
	v_mfma_f32_16x16x32_bf16 v[16:19], v[198:201], v[222:225], v[16:19]
	v_mfma_f32_16x16x32_bf16 v[4:7], v[190:193], v[230:233], v[4:7]
	v_mfma_f32_16x16x32_bf16 v[0:3], v[198:201], v[230:233], v[0:3]
	v_mfma_f32_16x16x32_bf16 v[52:55], v[194:197], v[210:213], v[52:55]
	v_mfma_f32_16x16x32_bf16 v[48:51], v[202:205], v[210:213], v[48:51]
	v_mfma_f32_16x16x32_bf16 v[36:39], v[194:197], v[218:221], v[36:39]
	v_mfma_f32_16x16x32_bf16 v[32:35], v[202:205], v[218:221], v[32:35]
	v_mfma_f32_16x16x32_bf16 v[20:23], v[194:197], v[226:229], v[20:23]
	v_mfma_f32_16x16x32_bf16 v[16:19], v[202:205], v[226:229], v[16:19]
	v_mfma_f32_16x16x32_bf16 v[4:7], v[194:197], v[242:245], v[4:7]
	v_mfma_f32_16x16x32_bf16 v[0:3], v[202:205], v[242:245], v[0:3]
	s_setprio 0
	s_barrier
	s_setprio 2
	s_add_i32 s59, s59, 2
	s_add_u32 s14, s14, 0x100
	s_addc_u32 s15, s15, 0
	s_add_u32 s57, s57, 0x100
	s_addc_u32 s58, s58, 0
	s_cmp_gt_u32 s59, 13
	s_cbranch_scc0 .LBB0_449
	s_and_b64 vcc, exec, s[18:19]
	s_cbranch_vccz .LBB0_454
	s_barrier
	v_lshl_add_u32 v146, s54, 8, v150
	s_cmp_gt_i32 s53, 7
	s_mov_b64 s[14:15], -1
	s_cbranch_scc1 .LBB0_455

.LBB0_490:
	s_add_i32 s66, s6, 2
	s_add_u32 s67, s4, 0x80
	s_addc_u32 s7, s5, 0
	s_add_i32 s70, 0, 0x10000
	s_cmp_eq_u32 s60, s6
	s_cselect_b32 s7, s43, s7
	s_cselect_b32 s6, s42, s67
	v_add_u32_e32 v148, s70, v151
	s_cselect_b32 s69, s45, s15
	s_cselect_b32 s68, s44, s14
	s_add_i32 s67, 0, 0x14000
	ds_read_b128 v[140:143], v148
	ds_read_b128 v[144:147], v148 offset:1024
	ds_read_b128 v[162:165], v148 offset:2048
	ds_read_b128 v[166:169], v148 offset:3072
	v_add_u32_e32 v148, s67, v151
	ds_read_b128 v[170:173], v148
	ds_read_b128 v[186:189], v148 offset:1024
	ds_read_b128 v[190:193], v148 offset:2048
	ds_read_b128 v[194:197], v148 offset:3072
	v_lshl_add_u64 v[148:149], s[4:5], 0, v[136:137]
	s_add_i32 m0, s52, 0xc000
	ds_read_b128 v[198:201], v153
	ds_read_b128 v[202:205], v153 offset:1024
	ds_read_b128 v[206:209], v153 offset:2048
	ds_read_b128 v[210:213], v153 offset:3072
	ds_read_b128 v[214:217], v153 offset:4096
	ds_read_b128 v[218:221], v153 offset:5120
	ds_read_b128 v[222:225], v153 offset:6144
	ds_read_b128 v[226:229], v153 offset:7168
	global_load_lds_dwordx4 v[148:149], off
	v_lshl_add_u64 v[148:149], s[4:5], 0, v[138:139]
	s_add_i32 m0, s52, 0xe000
	s_nop 0
	global_load_lds_dwordx4 v[148:149], off
	s_waitcnt vmcnt(8) lgkmcnt(0)
	s_barrier
	s_setprio 1
	v_mfma_f32_16x16x32_bf16 v[126:129], v[140:143], v[198:201], v[126:129]
	v_mfma_f32_16x16x32_bf16 v[122:125], v[162:165], v[198:201], v[122:125]
	v_mfma_f32_16x16x32_bf16 v[110:113], v[140:143], v[206:209], v[110:113]
	v_mfma_f32_16x16x32_bf16 v[106:109], v[162:165], v[206:209], v[106:109]
	v_mfma_f32_16x16x32_bf16 v[92:95], v[140:143], v[214:217], v[92:95]
	v_mfma_f32_16x16x32_bf16 v[88:91], v[162:165], v[214:217], v[88:91]
	v_mfma_f32_16x16x32_bf16 v[76:79], v[140:143], v[222:225], v[76:79]
	v_mfma_f32_16x16x32_bf16 v[72:75], v[162:165], v[222:225], v[72:75]
	v_mfma_f32_16x16x32_bf16 v[126:129], v[144:147], v[202:205], v[126:129]
	v_mfma_f32_16x16x32_bf16 v[122:125], v[166:169], v[202:205], v[122:125]
	v_mfma_f32_16x16x32_bf16 v[110:113], v[144:147], v[210:213], v[110:113]
	v_mfma_f32_16x16x32_bf16 v[106:109], v[166:169], v[210:213], v[106:109]
	v_mfma_f32_16x16x32_bf16 v[92:95], v[144:147], v[218:221], v[92:95]
	v_mfma_f32_16x16x32_bf16 v[88:91], v[166:169], v[218:221], v[88:91]
	v_mfma_f32_16x16x32_bf16 v[76:79], v[144:147], v[226:229], v[76:79]
	v_mfma_f32_16x16x32_bf16 v[72:75], v[166:169], v[226:229], v[72:75]
	s_setprio 0
	s_setprio 1
	v_mfma_f32_16x16x32_bf16 v[118:121], v[170:173], v[198:201], v[118:121]
	v_mfma_f32_16x16x32_bf16 v[114:117], v[190:193], v[198:201], v[114:117]
	v_mfma_f32_16x16x32_bf16 v[102:105], v[170:173], v[206:209], v[102:105]
	v_mfma_f32_16x16x32_bf16 v[98:101], v[190:193], v[206:209], v[98:101]
	v_mfma_f32_16x16x32_bf16 v[84:87], v[170:173], v[214:217], v[84:87]
	v_mfma_f32_16x16x32_bf16 v[80:83], v[190:193], v[214:217], v[80:83]
	v_mfma_f32_16x16x32_bf16 v[68:71], v[170:173], v[222:225], v[68:71]
	v_mfma_f32_16x16x32_bf16 v[64:67], v[190:193], v[222:225], v[64:67]
	v_mfma_f32_16x16x32_bf16 v[118:121], v[186:189], v[202:205], v[118:121]
	v_mfma_f32_16x16x32_bf16 v[114:117], v[194:197], v[202:205], v[114:117]
	v_mfma_f32_16x16x32_bf16 v[102:105], v[186:189], v[210:213], v[102:105]
	v_mfma_f32_16x16x32_bf16 v[98:101], v[194:197], v[210:213], v[98:101]
	v_mfma_f32_16x16x32_bf16 v[84:87], v[186:189], v[218:221], v[84:87]
	v_mfma_f32_16x16x32_bf16 v[80:83], v[194:197], v[218:221], v[80:83]
	v_mfma_f32_16x16x32_bf16 v[68:71], v[186:189], v[226:229], v[68:71]
	v_mfma_f32_16x16x32_bf16 v[64:67], v[194:197], v[226:229], v[64:67]
	s_setprio 0
	s_barrier
	s_setprio 2
	s_add_i32 s70, s70, s51
	v_lshl_add_u64 v[148:149], s[68:69], 0, v[96:97]
	s_mov_b32 m0, s70
	ds_read_b128 v[198:201], v153 offset:16384
	ds_read_b128 v[202:205], v153 offset:17408
	ds_read_b128 v[206:209], v153 offset:18432
	ds_read_b128 v[210:213], v153 offset:19456
	ds_read_b128 v[214:217], v153 offset:20480
	ds_read_b128 v[218:221], v153 offset:21504
	ds_read_b128 v[222:225], v153 offset:22528
	ds_read_b128 v[226:229], v153 offset:23552
	global_load_lds_dwordx4 v[148:149], off
	s_add_i32 m0, s70, 0x2000
	v_lshl_add_u64 v[154:155], s[68:69], 0, v[130:131]
	s_add_u32 s68, s68, s46
	s_addc_u32 s69, s69, 0
	s_add_i32 s67, s67, s51
	global_load_lds_dwordx4 v[154:155], off
	v_lshl_add_u64 v[156:157], s[68:69], 0, v[96:97]
	s_mov_b32 m0, s67
	v_lshl_add_u64 v[158:159], s[68:69], 0, v[130:131]
	global_load_lds_dwordx4 v[156:157], off
	s_add_i32 m0, s67, 0x2000
	v_lshl_add_u64 v[182:183], s[6:7], 0, v[134:135]
	global_load_lds_dwordx4 v[158:159], off
	s_mov_b32 m0, s52
	v_lshl_add_u64 v[184:185], s[6:7], 0, v[132:133]
	global_load_lds_dwordx4 v[182:183], off
	s_mov_b32 m0, s53
	s_nop 0
	global_load_lds_dwordx4 v[184:185], off
	s_waitcnt vmcnt(8) lgkmcnt(0)
	s_barrier
	s_setprio 1
	v_mfma_f32_16x16x32_bf16 v[60:63], v[140:143], v[198:201], v[60:63]
	v_mfma_f32_16x16x32_bf16 v[56:59], v[162:165], v[198:201], v[56:59]
	v_mfma_f32_16x16x32_bf16 v[44:47], v[140:143], v[206:209], v[44:47]
	v_mfma_f32_16x16x32_bf16 v[40:43], v[162:165], v[206:209], v[40:43]
	v_mfma_f32_16x16x32_bf16 v[28:31], v[140:143], v[214:217], v[28:31]
	v_mfma_f32_16x16x32_bf16 v[24:27], v[162:165], v[214:217], v[24:27]
	v_mfma_f32_16x16x32_bf16 v[12:15], v[140:143], v[222:225], v[12:15]
	v_mfma_f32_16x16x32_bf16 v[8:11], v[162:165], v[222:225], v[8:11]
	v_mfma_f32_16x16x32_bf16 v[60:63], v[144:147], v[202:205], v[60:63]
	v_mfma_f32_16x16x32_bf16 v[56:59], v[166:169], v[202:205], v[56:59]
	v_mfma_f32_16x16x32_bf16 v[44:47], v[144:147], v[210:213], v[44:47]
	v_mfma_f32_16x16x32_bf16 v[40:43], v[166:169], v[210:213], v[40:43]
	v_mfma_f32_16x16x32_bf16 v[28:31], v[144:147], v[218:221], v[28:31]
	v_mfma_f32_16x16x32_bf16 v[24:27], v[166:169], v[218:221], v[24:27]
	v_mfma_f32_16x16x32_bf16 v[12:15], v[144:147], v[226:229], v[12:15]
	v_mfma_f32_16x16x32_bf16 v[8:11], v[166:169], v[226:229], v[8:11]
	s_setprio 0
	s_setprio 1
	v_mfma_f32_16x16x32_bf16 v[52:55], v[170:173], v[198:201], v[52:55]
	v_mfma_f32_16x16x32_bf16 v[48:51], v[190:193], v[198:201], v[48:51]
	v_mfma_f32_16x16x32_bf16 v[36:39], v[170:173], v[206:209], v[36:39]
	v_mfma_f32_16x16x32_bf16 v[32:35], v[190:193], v[206:209], v[32:35]
	v_mfma_f32_16x16x32_bf16 v[20:23], v[170:173], v[214:217], v[20:23]
	v_mfma_f32_16x16x32_bf16 v[16:19], v[190:193], v[214:217], v[16:19]
	v_mfma_f32_16x16x32_bf16 v[4:7], v[170:173], v[222:225], v[4:7]
	v_mfma_f32_16x16x32_bf16 v[0:3], v[190:193], v[222:225], v[0:3]
	v_mfma_f32_16x16x32_bf16 v[52:55], v[186:189], v[202:205], v[52:55]
	v_mfma_f32_16x16x32_bf16 v[48:51], v[194:197], v[202:205], v[48:51]
	v_mfma_f32_16x16x32_bf16 v[36:39], v[186:189], v[210:213], v[36:39]
	v_mfma_f32_16x16x32_bf16 v[32:35], v[194:197], v[210:213], v[32:35]
	v_mfma_f32_16x16x32_bf16 v[20:23], v[186:189], v[218:221], v[20:23]
	v_mfma_f32_16x16x32_bf16 v[16:19], v[194:197], v[218:221], v[16:19]
	v_mfma_f32_16x16x32_bf16 v[4:7], v[186:189], v[226:229], v[4:7]
	v_mfma_f32_16x16x32_bf16 v[0:3], v[194:197], v[226:229], v[0:3]
	s_setprio 0
	s_barrier
	s_setprio 2
	s_add_i32 s67, 0, 0x18000
	s_add_i32 s68, 0, 0x1c000
	v_add_u32_e32 v166, s67, v151
	v_add_u32_e32 v194, s68, v151
	ds_read_b128 v[140:143], v166
	ds_read_b128 v[144:147], v166 offset:1024
	ds_read_b128 v[162:165], v166 offset:2048
	ds_read_b128 v[166:169], v166 offset:3072
	ds_read_b128 v[170:173], v194
	ds_read_b128 v[186:189], v194 offset:1024
	ds_read_b128 v[190:193], v194 offset:2048
	ds_read_b128 v[194:197], v194 offset:3072
	s_add_u32 s6, s6, s46
	s_addc_u32 s7, s7, 0
	s_mov_b32 m0, s54
	v_lshl_add_u64 v[230:231], s[6:7], 0, v[134:135]
	ds_read_b128 v[198:201], v153 offset:32768
	ds_read_b128 v[202:205], v153 offset:33792
	ds_read_b128 v[206:209], v153 offset:34816
	ds_read_b128 v[210:213], v153 offset:35840
	ds_read_b128 v[214:217], v153 offset:36864
	ds_read_b128 v[218:221], v153 offset:37888
	ds_read_b128 v[222:225], v153 offset:38912
	ds_read_b128 v[226:229], v153 offset:39936
	global_load_lds_dwordx4 v[230:231], off
	v_lshl_add_u64 v[230:231], s[6:7], 0, v[132:133]
	s_mov_b32 m0, s55
	s_nop 0
	global_load_lds_dwordx4 v[230:231], off
	s_waitcnt vmcnt(8) lgkmcnt(0)
	s_barrier
	s_setprio 1
	v_mfma_f32_16x16x32_bf16 v[126:129], v[140:143], v[198:201], v[126:129]
	v_mfma_f32_16x16x32_bf16 v[122:125], v[162:165], v[198:201], v[122:125]
	v_mfma_f32_16x16x32_bf16 v[110:113], v[140:143], v[206:209], v[110:113]
	v_mfma_f32_16x16x32_bf16 v[106:109], v[162:165], v[206:209], v[106:109]
	v_mfma_f32_16x16x32_bf16 v[92:95], v[140:143], v[214:217], v[92:95]
	v_mfma_f32_16x16x32_bf16 v[88:91], v[162:165], v[214:217], v[88:91]
	v_mfma_f32_16x16x32_bf16 v[76:79], v[140:143], v[222:225], v[76:79]
	v_mfma_f32_16x16x32_bf16 v[72:75], v[162:165], v[222:225], v[72:75]
	v_mfma_f32_16x16x32_bf16 v[126:129], v[144:147], v[202:205], v[126:129]
	v_mfma_f32_16x16x32_bf16 v[122:125], v[166:169], v[202:205], v[122:125]
	v_mfma_f32_16x16x32_bf16 v[110:113], v[144:147], v[210:213], v[110:113]
	v_mfma_f32_16x16x32_bf16 v[106:109], v[166:169], v[210:213], v[106:109]
	v_mfma_f32_16x16x32_bf16 v[92:95], v[144:147], v[218:221], v[92:95]
	v_mfma_f32_16x16x32_bf16 v[88:91], v[166:169], v[218:221], v[88:91]
	v_mfma_f32_16x16x32_bf16 v[76:79], v[144:147], v[226:229], v[76:79]
	v_mfma_f32_16x16x32_bf16 v[72:75], v[166:169], v[226:229], v[72:75]
	s_setprio 0
	s_setprio 1
	v_mfma_f32_16x16x32_bf16 v[118:121], v[170:173], v[198:201], v[118:121]
	v_mfma_f32_16x16x32_bf16 v[114:117], v[190:193], v[198:201], v[114:117]
	v_mfma_f32_16x16x32_bf16 v[102:105], v[170:173], v[206:209], v[102:105]
	v_mfma_f32_16x16x32_bf16 v[98:101], v[190:193], v[206:209], v[98:101]
	v_mfma_f32_16x16x32_bf16 v[84:87], v[170:173], v[214:217], v[84:87]
	v_mfma_f32_16x16x32_bf16 v[80:83], v[190:193], v[214:217], v[80:83]
	v_mfma_f32_16x16x32_bf16 v[68:71], v[170:173], v[222:225], v[68:71]
	v_mfma_f32_16x16x32_bf16 v[64:67], v[190:193], v[222:225], v[64:67]
	v_mfma_f32_16x16x32_bf16 v[118:121], v[186:189], v[202:205], v[118:121]
	v_mfma_f32_16x16x32_bf16 v[114:117], v[194:197], v[202:205], v[114:117]
	v_mfma_f32_16x16x32_bf16 v[102:105], v[186:189], v[210:213], v[102:105]
	v_mfma_f32_16x16x32_bf16 v[98:101], v[194:197], v[210:213], v[98:101]
	v_mfma_f32_16x16x32_bf16 v[84:87], v[186:189], v[218:221], v[84:87]
	v_mfma_f32_16x16x32_bf16 v[80:83], v[194:197], v[218:221], v[80:83]
	v_mfma_f32_16x16x32_bf16 v[68:71], v[186:189], v[226:229], v[68:71]
	v_mfma_f32_16x16x32_bf16 v[64:67], v[194:197], v[226:229], v[64:67]
	s_setprio 0
	s_barrier
	s_setprio 2
	s_add_i32 s6, s67, s51
	v_lshl_add_u64 v[148:149], v[148:149], 0, s[16:17]
	s_mov_b32 m0, s6
	ds_read_b128 v[198:201], v153 offset:49152
	ds_read_b128 v[202:205], v153 offset:50176
	ds_read_b128 v[206:209], v153 offset:51200
	ds_read_b128 v[210:213], v153 offset:52224
	ds_read_b128 v[214:217], v153 offset:53248
	ds_read_b128 v[218:221], v153 offset:54272
	ds_read_b128 v[222:225], v153 offset:55296
	ds_read_b128 v[226:229], v153 offset:56320
	global_load_lds_dwordx4 v[148:149], off
	v_lshl_add_u64 v[148:149], v[154:155], 0, s[16:17]
	s_add_i32 m0, s6, 0x2000
	s_add_i32 s6, s68, s51
	global_load_lds_dwordx4 v[148:149], off
	v_lshl_add_u64 v[148:149], v[156:157], 0, s[16:17]
	s_mov_b32 m0, s6
	s_nop 0
	global_load_lds_dwordx4 v[148:149], off
	v_lshl_add_u64 v[148:149], v[158:159], 0, s[16:17]
	s_add_i32 m0, s6, 0x2000
	s_nop 0
	global_load_lds_dwordx4 v[148:149], off
	v_lshl_add_u64 v[148:149], v[182:183], 0, s[16:17]
	s_mov_b32 m0, s56
	s_nop 0
	global_load_lds_dwordx4 v[148:149], off
	v_lshl_add_u64 v[148:149], v[184:185], 0, s[16:17]
	s_mov_b32 m0, s57
	s_nop 0
	global_load_lds_dwordx4 v[148:149], off
	s_waitcnt vmcnt(8) lgkmcnt(0)
	s_barrier
	s_setprio 1
	v_mfma_f32_16x16x32_bf16 v[60:63], v[140:143], v[198:201], v[60:63]
	v_mfma_f32_16x16x32_bf16 v[56:59], v[162:165], v[198:201], v[56:59]
	v_mfma_f32_16x16x32_bf16 v[44:47], v[140:143], v[206:209], v[44:47]
	v_mfma_f32_16x16x32_bf16 v[40:43], v[162:165], v[206:209], v[40:43]
	v_mfma_f32_16x16x32_bf16 v[28:31], v[140:143], v[214:217], v[28:31]
	v_mfma_f32_16x16x32_bf16 v[24:27], v[162:165], v[214:217], v[24:27]
	v_mfma_f32_16x16x32_bf16 v[12:15], v[140:143], v[222:225], v[12:15]
	v_mfma_f32_16x16x32_bf16 v[8:11], v[162:165], v[222:225], v[8:11]
	v_mfma_f32_16x16x32_bf16 v[60:63], v[144:147], v[202:205], v[60:63]
	v_mfma_f32_16x16x32_bf16 v[56:59], v[166:169], v[202:205], v[56:59]
	v_mfma_f32_16x16x32_bf16 v[44:47], v[144:147], v[210:213], v[44:47]
	v_mfma_f32_16x16x32_bf16 v[40:43], v[166:169], v[210:213], v[40:43]
	v_mfma_f32_16x16x32_bf16 v[28:31], v[144:147], v[218:221], v[28:31]
	v_mfma_f32_16x16x32_bf16 v[24:27], v[166:169], v[218:221], v[24:27]
	v_mfma_f32_16x16x32_bf16 v[12:15], v[144:147], v[226:229], v[12:15]
	v_mfma_f32_16x16x32_bf16 v[8:11], v[166:169], v[226:229], v[8:11]
	s_setprio 0
	s_setprio 1
	v_mfma_f32_16x16x32_bf16 v[52:55], v[170:173], v[198:201], v[52:55]
	v_mfma_f32_16x16x32_bf16 v[48:51], v[190:193], v[198:201], v[48:51]
	v_mfma_f32_16x16x32_bf16 v[36:39], v[170:173], v[206:209], v[36:39]
	v_mfma_f32_16x16x32_bf16 v[32:35], v[190:193], v[206:209], v[32:35]
	v_mfma_f32_16x16x32_bf16 v[20:23], v[170:173], v[214:217], v[20:23]
	v_mfma_f32_16x16x32_bf16 v[16:19], v[190:193], v[214:217], v[16:19]
	v_mfma_f32_16x16x32_bf16 v[4:7], v[170:173], v[222:225], v[4:7]
	v_mfma_f32_16x16x32_bf16 v[0:3], v[190:193], v[222:225], v[0:3]
	v_mfma_f32_16x16x32_bf16 v[52:55], v[186:189], v[202:205], v[52:55]
	v_mfma_f32_16x16x32_bf16 v[48:51], v[194:197], v[202:205], v[48:51]
	v_mfma_f32_16x16x32_bf16 v[36:39], v[186:189], v[210:213], v[36:39]
	v_mfma_f32_16x16x32_bf16 v[32:35], v[194:197], v[210:213], v[32:35]
	v_mfma_f32_16x16x32_bf16 v[20:23], v[186:189], v[218:221], v[20:23]
	v_mfma_f32_16x16x32_bf16 v[16:19], v[194:197], v[218:221], v[16:19]
	v_mfma_f32_16x16x32_bf16 v[4:7], v[186:189], v[226:229], v[4:7]
	v_mfma_f32_16x16x32_bf16 v[0:3], v[194:197], v[226:229], v[0:3]
	s_setprio 0
	s_barrier
	s_setprio 2
	s_add_u32 s4, s4, 0x100
	s_addc_u32 s5, s5, 0
	s_add_u32 s14, s14, 0x100
	s_addc_u32 s15, s15, 0
	s_cmp_ge_u32 s66, s59
	s_mov_b32 s6, s66
	s_cbranch_scc0 .LBB0_490
	s_and_b64 vcc, exec, s[36:37]
	s_cbranch_vccz .LBB0_493
	s_barrier
